# MLP-up squared-ReLU epilogue stores write-through (sc1) so the grid barrier's L2 write-back finds less dirty data; fused-epilogue L1 invalidate restored
# baseline (speedup 1.0000x reference)
; #define PG8_STAGE(bufoff, gbase, voff) do { _Pragma("unroll") for (int _i = 0; _i < 2; ++_i) \
;         __builtin_amdgcn_global_load_lds((const unsigned*)((const char*)(gbase) + (voff)[_i]), (LAS unsigned*)(lds + (bufoff) + ldsw + _i * 8192), 16, 0, 0); } while (0)
; #define PG8_LDA(dst, b, h) do { _Pragma("unroll") for (int m = 0; m < 4; ++m) _Pragma("unroll") for (int k = 0; k < 2; ++k) dst[m][k] = *(const LAS bf16x8*)(lds + PG8_SA(b, h) + aoff + m * 2048 + k * 1024); } while (0)
; #define PG8_LDB(dst, b, h) do { _Pragma("unroll") for (int n = 0; n < 2; ++n) _Pragma("unroll") for (int k = 0; k < 2; ++k) dst[n][k] = *(const LAS bf16x8*)(lds + PG8_SB(b, h) + boff + n * 2048 + k * 1024); } while (0)
; #define PG8_WAIT_V(n) asm volatile("s_waitcnt vmcnt(" #n ")" ::: "memory")
; #define PG8_WAIT_L(n) asm volatile("s_waitcnt lgkmcnt(" #n ")" ::: "memory")
; #define PG8_BAR __builtin_amdgcn_s_barrier()
; template <class Epi>
; __device__ __forceinline__ void gemm_phase(LAS unsigned char* lds, const bf16_t* A, int lda, const bf16_t* Bt, int ldb, int M, int N, int K, int asel, const Epi& E, const int fixed_round = -1) {
;     ...
;             PG8_LDB(B0, 0, 0); PG8_SCHED; PG8_LDA(At, 0, 0); PG8_STAGE(PG8_SA(1, 1), a1 + hstepA, voffA);
;             PG8_WAIT_L(8); PG8_BAR; PG8_WAIT_L(0); PG8_MMA(0, 0, At, B0); PG8_BAR; PG8_SCHED;
;             PG8_LDB(B1, 0, 1); PG8_STAGE(PG8_SB(0, 0), b2, voffB);
;             PG8_BAR; PG8_WAIT_L(0); PG8_MMA(0, 1, At, B1); PG8_BAR;
;             PG8_LDA(At, 0, 1); PG8_STAGE(PG8_SA(0, 0), a2, voffA);
;             PG8_BAR; PG8_WAIT_L(0); PG8_MMA(1, 0, At, B0); PG8_BAR; PG8_SCHED;
;             PG8_STAGE(PG8_SB(0, 1), b2 + hstepB, voffB);
;             PG8_WAIT_V(6); PG8_BAR; PG8_MMA(1, 1, At, B1); PG8_BAR;
;             PG8_LDB(B0, 1, 0); PG8_SCHED; PG8_LDA(At, 1, 0); PG8_STAGE(PG8_SA(0, 1), a2 + hstepA, voffA);
;             PG8_WAIT_L(8); PG8_BAR; PG8_WAIT_L(0); PG8_MMA(0, 0, At, B0); PG8_BAR; PG8_SCHED;
;             PG8_LDB(B1, 1, 1); PG8_STAGE(PG8_SB(1, 0), b3, voffB);
;             PG8_BAR; PG8_WAIT_L(0); PG8_MMA(0, 1, At, B1); PG8_BAR;
;             PG8_LDA(At, 1, 1); PG8_STAGE(PG8_SA(1, 0), a3, voffA);
;             PG8_BAR; PG8_WAIT_L(0); PG8_MMA(1, 0, At, B0); PG8_BAR; PG8_SCHED;
;             PG8_STAGE(PG8_SB(1, 1), b3 + hstepB, voffB);
;             PG8_WAIT_V(6); PG8_BAR; PG8_MMA(1, 1, At, B1); PG8_BAR;
.LBB0_591:
	ds_read_b128 v[152:155], v149
	ds_read_b128 v[156:159], v149 offset:1024
	ds_read_b128 v[160:163], v149 offset:2048
	ds_read_b128 v[164:167], v149 offset:3072
	s_add_u32 s28, s30, 0xfff80080
	s_addc_u32 s29, s31, -1
	s_cmp_eq_u32 s56, 28
	s_cselect_b32 s37, s7, s29
	s_cselect_b32 s36, s52, s28
	s_cselect_b32 s35, s5, s55
	s_cselect_b32 s34, s53, s54
	s_add_i32 m0, s27, 0xc000
	ds_read_b128 v[168:171], v150
	ds_read_b128 v[172:175], v150 offset:1024
	ds_read_b128 v[176:179], v150 offset:2048
	ds_read_b128 v[180:183], v150 offset:3072
	ds_read_b128 v[184:187], v150 offset:4096
	ds_read_b128 v[188:191], v150 offset:5120
	ds_read_b128 v[192:195], v150 offset:6144
	ds_read_b128 v[196:199], v150 offset:7168
	global_load_lds_dwordx4 v136, s[30:31]
	s_add_i32 m0, s27, 0xe000
	s_nop 0
	global_load_lds_dwordx4 v138, s[30:31]
	s_waitcnt lgkmcnt(8)
	s_barrier
	s_waitcnt lgkmcnt(0)
	s_setprio 1
	s_waitcnt lgkmcnt(0)
	v_mfma_f32_16x16x32_bf16 v[124:127], v[152:155], v[168:171], v[124:127]
	v_mfma_f32_16x16x32_bf16 v[120:123], v[160:163], v[168:171], v[120:123]
	v_mfma_f32_16x16x32_bf16 v[108:111], v[152:155], v[176:179], v[108:111]
	v_mfma_f32_16x16x32_bf16 v[104:107], v[160:163], v[176:179], v[104:107]
	v_mfma_f32_16x16x32_bf16 v[92:95], v[152:155], v[184:187], v[92:95]
	v_mfma_f32_16x16x32_bf16 v[88:91], v[160:163], v[184:187], v[88:91]
	v_mfma_f32_16x16x32_bf16 v[76:79], v[152:155], v[192:195], v[76:79]
	v_mfma_f32_16x16x32_bf16 v[72:75], v[160:163], v[192:195], v[72:75]
	v_mfma_f32_16x16x32_bf16 v[124:127], v[156:159], v[172:175], v[124:127]
	v_mfma_f32_16x16x32_bf16 v[120:123], v[164:167], v[172:175], v[120:123]
	v_mfma_f32_16x16x32_bf16 v[108:111], v[156:159], v[180:183], v[108:111]
	v_mfma_f32_16x16x32_bf16 v[104:107], v[164:167], v[180:183], v[104:107]
	v_mfma_f32_16x16x32_bf16 v[92:95], v[156:159], v[188:191], v[92:95]
	v_mfma_f32_16x16x32_bf16 v[88:91], v[164:167], v[188:191], v[88:91]
	v_mfma_f32_16x16x32_bf16 v[76:79], v[156:159], v[196:199], v[76:79]
	v_mfma_f32_16x16x32_bf16 v[72:75], v[164:167], v[196:199], v[72:75]
	s_setprio 0
	s_barrier
	s_add_i32 s28, s81, s42
	s_add_u32 s98, s34, s2
	s_addc_u32 s99, s35, s3
	s_mov_b32 m0, s28
	ds_read_b128 v[202:205], v151
	ds_read_b128 v[206:209], v151 offset:1024
	ds_read_b128 v[210:213], v151 offset:2048
	ds_read_b128 v[214:217], v151 offset:3072
	global_load_lds_dwordx4 v130, s[34:35]
	s_add_i32 m0, s28, 0x2000
	s_nop 0
	global_load_lds_dwordx4 v134, s[34:35]
	s_barrier
	s_waitcnt lgkmcnt(0)
	s_setprio 1
	s_waitcnt lgkmcnt(0)
	v_mfma_f32_16x16x32_bf16 v[116:119], v[202:205], v[168:171], v[116:119]
	v_mfma_f32_16x16x32_bf16 v[112:115], v[210:213], v[168:171], v[112:115]
	v_mfma_f32_16x16x32_bf16 v[100:103], v[202:205], v[176:179], v[100:103]
	v_mfma_f32_16x16x32_bf16 v[96:99], v[210:213], v[176:179], v[96:99]
	v_mfma_f32_16x16x32_bf16 v[84:87], v[202:205], v[184:187], v[84:87]
	v_mfma_f32_16x16x32_bf16 v[80:83], v[210:213], v[184:187], v[80:83]
	v_mfma_f32_16x16x32_bf16 v[68:71], v[202:205], v[192:195], v[68:71]
	v_mfma_f32_16x16x32_bf16 v[64:67], v[210:213], v[192:195], v[64:67]
	v_mfma_f32_16x16x32_bf16 v[116:119], v[206:209], v[172:175], v[116:119]
	v_mfma_f32_16x16x32_bf16 v[112:115], v[214:217], v[172:175], v[112:115]
	v_mfma_f32_16x16x32_bf16 v[100:103], v[206:209], v[180:183], v[100:103]
	v_mfma_f32_16x16x32_bf16 v[96:99], v[214:217], v[180:183], v[96:99]
	v_mfma_f32_16x16x32_bf16 v[84:87], v[206:209], v[188:191], v[84:87]
	v_mfma_f32_16x16x32_bf16 v[80:83], v[214:217], v[188:191], v[80:83]
	v_mfma_f32_16x16x32_bf16 v[68:71], v[206:209], v[196:199], v[68:71]
	v_mfma_f32_16x16x32_bf16 v[64:67], v[214:217], v[196:199], v[64:67]
	s_setprio 0
	s_mov_b32 m0, s27
	s_add_u32 s100, s36, s2
	s_addc_u32 s101, s37, s3
	s_barrier
	ds_read_b128 v[168:171], v150 offset:16384
	ds_read_b128 v[172:175], v150 offset:17408
	ds_read_b128 v[176:179], v150 offset:18432
	ds_read_b128 v[180:183], v150 offset:19456
	ds_read_b128 v[184:187], v150 offset:20480
	ds_read_b128 v[188:191], v150 offset:21504
	ds_read_b128 v[192:195], v150 offset:22528
	ds_read_b128 v[196:199], v150 offset:23552
	global_load_lds_dwordx4 v128, s[36:37]
	s_mov_b32 m0, s43
	s_nop 0
	global_load_lds_dwordx4 v132, s[36:37]
	s_barrier
	s_waitcnt lgkmcnt(0)
	s_setprio 1
	s_waitcnt lgkmcnt(0)
	v_mfma_f32_16x16x32_bf16 v[60:63], v[152:155], v[168:171], v[60:63]
	v_mfma_f32_16x16x32_bf16 v[56:59], v[160:163], v[168:171], v[56:59]
	v_mfma_f32_16x16x32_bf16 v[44:47], v[152:155], v[176:179], v[44:47]
	v_mfma_f32_16x16x32_bf16 v[40:43], v[160:163], v[176:179], v[40:43]
	v_mfma_f32_16x16x32_bf16 v[28:31], v[152:155], v[184:187], v[28:31]
	v_mfma_f32_16x16x32_bf16 v[24:27], v[160:163], v[184:187], v[24:27]
	v_mfma_f32_16x16x32_bf16 v[12:15], v[152:155], v[192:195], v[12:15]
	v_mfma_f32_16x16x32_bf16 v[8:11], v[160:163], v[192:195], v[8:11]
	v_mfma_f32_16x16x32_bf16 v[60:63], v[156:159], v[172:175], v[60:63]
	v_mfma_f32_16x16x32_bf16 v[56:59], v[164:167], v[172:175], v[56:59]
	v_mfma_f32_16x16x32_bf16 v[44:47], v[156:159], v[180:183], v[44:47]
	v_mfma_f32_16x16x32_bf16 v[40:43], v[164:167], v[180:183], v[40:43]
	v_mfma_f32_16x16x32_bf16 v[28:31], v[156:159], v[188:191], v[28:31]
	v_mfma_f32_16x16x32_bf16 v[24:27], v[164:167], v[188:191], v[24:27]
	v_mfma_f32_16x16x32_bf16 v[12:15], v[156:159], v[196:199], v[12:15]
	v_mfma_f32_16x16x32_bf16 v[8:11], v[164:167], v[196:199], v[8:11]
	s_setprio 0
	s_barrier
	s_add_u32 s28, s34, 0x80000
	s_addc_u32 s29, s35, 0
	s_add_i32 s57, s82, s42
	s_mov_b32 m0, s57
	s_nop 0
	global_load_lds_dwordx4 v130, s[28:29]
	s_add_i32 m0, s57, 0x2000
	s_nop 0
	global_load_lds_dwordx4 v134, s[28:29]
	s_waitcnt vmcnt(6)
	s_barrier
; #define PG8_STAGE(bufoff, gbase, voff) do { _Pragma("unroll") for (int _i = 0; _i < 2; ++_i) \
;         __builtin_amdgcn_global_load_lds((const unsigned*)((const char*)(gbase) + (voff)[_i]), (LAS unsigned*)(lds + (bufoff) + ldsw + _i * 8192), 16, 0, 0); } while (0)
; #define PG8_LDA(dst, b, h) do { _Pragma("unroll") for (int m = 0; m < 4; ++m) _Pragma("unroll") for (int k = 0; k < 2; ++k) dst[m][k] = *(const LAS bf16x8*)(lds + PG8_SA(b, h) + aoff + m * 2048 + k * 1024); } while (0)
; #define PG8_LDB(dst, b, h) do { _Pragma("unroll") for (int n = 0; n < 2; ++n) _Pragma("unroll") for (int k = 0; k < 2; ++k) dst[n][k] = *(const LAS bf16x8*)(lds + PG8_SB(b, h) + boff + n * 2048 + k * 1024); } while (0)
; #define PG8_WAIT_V(n) asm volatile("s_waitcnt vmcnt(" #n ")" ::: "memory")
; #define PG8_WAIT_L(n) asm volatile("s_waitcnt lgkmcnt(" #n ")" ::: "memory")
; #define PG8_BAR __builtin_amdgcn_s_barrier()
; template <class Epi>
; __device__ __forceinline__ void gemm_phase(LAS unsigned char* lds, const bf16_t* A, int lda, const bf16_t* Bt, int ldb, int M, int N, int K, int asel, const Epi& E, const int fixed_round = -1) {
;     ...
;             PG8_LDB(B0, 0, 0); PG8_SCHED; PG8_LDA(At, 0, 0); PG8_STAGE(PG8_SA(1, 1), a1 + hstepA, voffA);
;             PG8_WAIT_L(8); PG8_BAR; PG8_WAIT_L(0); PG8_MMA(0, 0, At, B0); PG8_BAR; PG8_SCHED;
;             PG8_LDB(B1, 0, 1); PG8_STAGE(PG8_SB(0, 0), b2, voffB);
;             PG8_BAR; PG8_WAIT_L(0); PG8_MMA(0, 1, At, B1); PG8_BAR;
;             PG8_LDA(At, 0, 1); PG8_STAGE(PG8_SA(0, 0), a2, voffA);
;             PG8_BAR; PG8_WAIT_L(0); PG8_MMA(1, 0, At, B0); PG8_BAR; PG8_SCHED;
;             PG8_STAGE(PG8_SB(0, 1), b2 + hstepB, voffB);
;             PG8_WAIT_V(6); PG8_BAR; PG8_MMA(1, 1, At, B1); PG8_BAR;
;             PG8_LDB(B0, 1, 0); PG8_SCHED; PG8_LDA(At, 1, 0); PG8_STAGE(PG8_SA(0, 1), a2 + hstepA, voffA);
;             PG8_WAIT_L(8); PG8_BAR; PG8_WAIT_L(0); PG8_MMA(0, 0, At, B0); PG8_BAR; PG8_SCHED;
;             PG8_LDB(B1, 1, 1); PG8_STAGE(PG8_SB(1, 0), b3, voffB);
;             PG8_BAR; PG8_WAIT_L(0); PG8_MMA(0, 1, At, B1); PG8_BAR;
;             PG8_LDA(At, 1, 1); PG8_STAGE(PG8_SA(1, 0), a3, voffA);
;             PG8_BAR; PG8_WAIT_L(0); PG8_MMA(1, 0, At, B0); PG8_BAR; PG8_SCHED;
;             PG8_STAGE(PG8_SB(1, 1), b3 + hstepB, voffB);
;             PG8_WAIT_V(6); PG8_BAR; PG8_MMA(1, 1, At, B1); PG8_BAR;
	s_setprio 1
	v_mfma_f32_16x16x32_bf16 v[52:55], v[202:205], v[168:171], v[52:55]
	v_mfma_f32_16x16x32_bf16 v[48:51], v[210:213], v[168:171], v[48:51]
	v_mfma_f32_16x16x32_bf16 v[36:39], v[202:205], v[176:179], v[36:39]
	v_mfma_f32_16x16x32_bf16 v[32:35], v[210:213], v[176:179], v[32:35]
	v_mfma_f32_16x16x32_bf16 v[20:23], v[202:205], v[184:187], v[20:23]
	v_mfma_f32_16x16x32_bf16 v[16:19], v[210:213], v[184:187], v[16:19]
	v_mfma_f32_16x16x32_bf16 v[4:7], v[202:205], v[192:195], v[4:7]
	v_mfma_f32_16x16x32_bf16 v[0:3], v[210:213], v[192:195], v[0:3]
	v_mfma_f32_16x16x32_bf16 v[52:55], v[206:209], v[172:175], v[52:55]
	v_mfma_f32_16x16x32_bf16 v[48:51], v[214:217], v[172:175], v[48:51]
	v_mfma_f32_16x16x32_bf16 v[36:39], v[206:209], v[180:183], v[36:39]
	v_mfma_f32_16x16x32_bf16 v[32:35], v[214:217], v[180:183], v[32:35]
	v_mfma_f32_16x16x32_bf16 v[20:23], v[206:209], v[188:191], v[20:23]
	v_mfma_f32_16x16x32_bf16 v[16:19], v[214:217], v[188:191], v[16:19]
	v_mfma_f32_16x16x32_bf16 v[4:7], v[206:209], v[196:199], v[4:7]
	v_mfma_f32_16x16x32_bf16 v[0:3], v[214:217], v[196:199], v[0:3]
	s_setprio 0
	v_add_u32_e32 v164, s83, v147
	s_barrier
	ds_read_b128 v[152:155], v164
	ds_read_b128 v[156:159], v164 offset:1024
	ds_read_b128 v[160:163], v164 offset:2048
	ds_read_b128 v[164:167], v164 offset:3072
	s_add_u32 s28, s36, 0x80000
	s_addc_u32 s29, s37, 0
	s_mov_b32 m0, s44
	ds_read_b128 v[168:171], v150 offset:32768
	ds_read_b128 v[172:175], v150 offset:33792
	ds_read_b128 v[176:179], v150 offset:34816
	ds_read_b128 v[180:183], v150 offset:35840
	ds_read_b128 v[184:187], v150 offset:36864
	ds_read_b128 v[188:191], v150 offset:37888
	ds_read_b128 v[192:195], v150 offset:38912
	ds_read_b128 v[196:199], v150 offset:39936
	global_load_lds_dwordx4 v128, s[28:29]
	s_mov_b32 m0, s45
	s_nop 0
	global_load_lds_dwordx4 v132, s[28:29]
	s_waitcnt lgkmcnt(8)
	s_barrier
	s_waitcnt lgkmcnt(0)
	s_setprio 1
	s_waitcnt lgkmcnt(0)
	v_mfma_f32_16x16x32_bf16 v[124:127], v[152:155], v[168:171], v[124:127]
	v_mfma_f32_16x16x32_bf16 v[120:123], v[160:163], v[168:171], v[120:123]
	v_mfma_f32_16x16x32_bf16 v[108:111], v[152:155], v[176:179], v[108:111]
	v_mfma_f32_16x16x32_bf16 v[104:107], v[160:163], v[176:179], v[104:107]
	v_mfma_f32_16x16x32_bf16 v[92:95], v[152:155], v[184:187], v[92:95]
	v_mfma_f32_16x16x32_bf16 v[88:91], v[160:163], v[184:187], v[88:91]
	v_mfma_f32_16x16x32_bf16 v[76:79], v[152:155], v[192:195], v[76:79]
	v_mfma_f32_16x16x32_bf16 v[72:75], v[160:163], v[192:195], v[72:75]
	v_mfma_f32_16x16x32_bf16 v[124:127], v[156:159], v[172:175], v[124:127]
	v_mfma_f32_16x16x32_bf16 v[120:123], v[164:167], v[172:175], v[120:123]
	v_mfma_f32_16x16x32_bf16 v[108:111], v[156:159], v[180:183], v[108:111]
	v_mfma_f32_16x16x32_bf16 v[104:107], v[164:167], v[180:183], v[104:107]
	v_mfma_f32_16x16x32_bf16 v[92:95], v[156:159], v[188:191], v[92:95]
	v_mfma_f32_16x16x32_bf16 v[88:91], v[164:167], v[188:191], v[88:91]
	v_mfma_f32_16x16x32_bf16 v[76:79], v[156:159], v[196:199], v[76:79]
	v_mfma_f32_16x16x32_bf16 v[72:75], v[164:167], v[196:199], v[72:75]
	s_setprio 0
	s_barrier
	s_add_i32 s28, s83, s42
	v_add_u32_e32 v214, s84, v147
	s_mov_b32 m0, s28
	ds_read_b128 v[202:205], v214
	ds_read_b128 v[206:209], v214 offset:1024
	ds_read_b128 v[210:213], v214 offset:2048
	ds_read_b128 v[214:217], v214 offset:3072
	global_load_lds_dwordx4 v130, s[98:99]
	s_add_i32 m0, s28, 0x2000
	s_nop 0
	global_load_lds_dwordx4 v134, s[98:99]
	s_barrier
	s_waitcnt lgkmcnt(0)
	s_setprio 1
	s_waitcnt lgkmcnt(0)
	v_mfma_f32_16x16x32_bf16 v[116:119], v[202:205], v[168:171], v[116:119]
	v_mfma_f32_16x16x32_bf16 v[112:115], v[210:213], v[168:171], v[112:115]
	v_mfma_f32_16x16x32_bf16 v[100:103], v[202:205], v[176:179], v[100:103]
	v_mfma_f32_16x16x32_bf16 v[96:99], v[210:213], v[176:179], v[96:99]
	v_mfma_f32_16x16x32_bf16 v[84:87], v[202:205], v[184:187], v[84:87]
	v_mfma_f32_16x16x32_bf16 v[80:83], v[210:213], v[184:187], v[80:83]
	v_mfma_f32_16x16x32_bf16 v[68:71], v[202:205], v[192:195], v[68:71]
	v_mfma_f32_16x16x32_bf16 v[64:67], v[210:213], v[192:195], v[64:67]
	v_mfma_f32_16x16x32_bf16 v[116:119], v[206:209], v[172:175], v[116:119]
	v_mfma_f32_16x16x32_bf16 v[112:115], v[214:217], v[172:175], v[112:115]
	v_mfma_f32_16x16x32_bf16 v[100:103], v[206:209], v[180:183], v[100:103]
	v_mfma_f32_16x16x32_bf16 v[96:99], v[214:217], v[180:183], v[96:99]
	v_mfma_f32_16x16x32_bf16 v[84:87], v[206:209], v[188:191], v[84:87]
	v_mfma_f32_16x16x32_bf16 v[80:83], v[214:217], v[188:191], v[80:83]
	v_mfma_f32_16x16x32_bf16 v[68:71], v[206:209], v[196:199], v[68:71]
	v_mfma_f32_16x16x32_bf16 v[64:67], v[214:217], v[196:199], v[64:67]
	s_setprio 0
	s_mov_b32 m0, s47
	s_barrier
	ds_read_b128 v[168:171], v150 offset:49152
	ds_read_b128 v[172:175], v150 offset:50176
	ds_read_b128 v[176:179], v150 offset:51200
	ds_read_b128 v[180:183], v150 offset:52224
	ds_read_b128 v[184:187], v150 offset:53248
	ds_read_b128 v[188:191], v150 offset:54272
	ds_read_b128 v[192:195], v150 offset:55296
	ds_read_b128 v[196:199], v150 offset:56320
	global_load_lds_dwordx4 v128, s[100:101]
	s_mov_b32 m0, s48
	s_nop 0
	global_load_lds_dwordx4 v132, s[100:101]
	s_barrier
; __device__ __forceinline__ unsigned cvt_pk_bf16(float lo, float hi) { const bf16x2_t r = __builtin_convertvector((f32x2){lo, hi}, bf16x2_t); return __builtin_bit_cast(unsigned, r); }
; #define PG8_STAGE(bufoff, gbase, voff) do { _Pragma("unroll") for (int _i = 0; _i < 2; ++_i) \
;         __builtin_amdgcn_global_load_lds((const unsigned*)((const char*)(gbase) + (voff)[_i]), (LAS unsigned*)(lds + (bufoff) + ldsw + _i * 8192), 16, 0, 0); } while (0)
; #define PG8_WAIT_V(n) asm volatile("s_waitcnt vmcnt(" #n ")" ::: "memory")
; #define PG8_BAR __builtin_amdgcn_s_barrier()
; template <class Epi>
; __device__ __forceinline__ void gemm_phase(LAS unsigned char* lds, const bf16_t* A, int lda, const bf16_t* Bt, int ldb, int M, int N, int K, int asel, const Epi& E, const int fixed_round = -1) {
;     ...
;             PG8_WAIT_V(6); PG8_BAR; PG8_MMA(1, 1, At, B1); PG8_BAR;
;             PG8_LDB(B0, 1, 0); PG8_SCHED; PG8_LDA(At, 1, 0); PG8_STAGE(PG8_SA(0, 1), a2 + hstepA, voffA);
;             PG8_WAIT_L(8); PG8_BAR; PG8_WAIT_L(0); PG8_MMA(0, 0, At, B0); PG8_BAR; PG8_SCHED;
;             PG8_LDB(B1, 1, 1); PG8_STAGE(PG8_SB(1, 0), b3, voffB);
;             PG8_BAR; PG8_WAIT_L(0); PG8_MMA(0, 1, At, B1); PG8_BAR;
;             PG8_LDA(At, 1, 1); PG8_STAGE(PG8_SA(1, 0), a3, voffA);
;             PG8_BAR; PG8_WAIT_L(0); PG8_MMA(1, 0, At, B0); PG8_BAR; PG8_SCHED;
;             PG8_STAGE(PG8_SB(1, 1), b3 + hstepB, voffB);
;             PG8_WAIT_V(6); PG8_BAR; PG8_MMA(1, 1, At, B1); PG8_BAR;
;     __device__ __forceinline__ void operator()(const AccT& acc, const Unit& u, int wr, int wc, int fr, int fq) const {
;         const int row0 = u.pm * BM + wr * 64 + fr, col0 = u.pn * BM + wc * 32 + 8 * fq;
; #pragma unroll
;         for (int ai = 0; ai < 2; ++ai)
; #pragma unroll
;             for (int m = 0; m < 4; ++m) { bf16_t* rowp = O + (size_t)(row0 + ai * HALF + m * 16) * DFF + col0;
; #pragma unroll
;                 for (int bj = 0; bj < 2; ++bj) { f32x4 v0 = acc[ai][bj][m][0], v1 = acc[ai][bj][m][1];
; #pragma unroll
;                     for (int j = 0; j < 4; ++j) { float a = fmaxf(v0[j], 0.f), b = fmaxf(v1[j], 0.f); v0[j] = a * a; v1[j] = b * b; }
;                     u32x4 w; w.x = cvt_pk_bf16(v0[0], v0[1]); w.y = cvt_pk_bf16(v0[2], v0[3]); w.z = cvt_pk_bf16(v1[0], v1[1]); w.w = cvt_pk_bf16(v1[2], v1[3]);
;                     *(u32x4*)(rowp + bj * HALF) = w; } }
	s_waitcnt lgkmcnt(0)
	s_setprio 1
	s_waitcnt lgkmcnt(0)
	v_mfma_f32_16x16x32_bf16 v[60:63], v[152:155], v[168:171], v[60:63]
	v_mfma_f32_16x16x32_bf16 v[56:59], v[160:163], v[168:171], v[56:59]
	v_mfma_f32_16x16x32_bf16 v[44:47], v[152:155], v[176:179], v[44:47]
	v_mfma_f32_16x16x32_bf16 v[40:43], v[160:163], v[176:179], v[40:43]
	v_mfma_f32_16x16x32_bf16 v[28:31], v[152:155], v[184:187], v[28:31]
	v_mfma_f32_16x16x32_bf16 v[24:27], v[160:163], v[184:187], v[24:27]
	v_mfma_f32_16x16x32_bf16 v[12:15], v[152:155], v[192:195], v[12:15]
	v_mfma_f32_16x16x32_bf16 v[8:11], v[160:163], v[192:195], v[8:11]
	v_mfma_f32_16x16x32_bf16 v[60:63], v[156:159], v[172:175], v[60:63]
	v_mfma_f32_16x16x32_bf16 v[56:59], v[164:167], v[172:175], v[56:59]
	v_mfma_f32_16x16x32_bf16 v[44:47], v[156:159], v[180:183], v[44:47]
	v_mfma_f32_16x16x32_bf16 v[40:43], v[164:167], v[180:183], v[40:43]
	v_mfma_f32_16x16x32_bf16 v[28:31], v[156:159], v[188:191], v[28:31]
	v_mfma_f32_16x16x32_bf16 v[24:27], v[164:167], v[188:191], v[24:27]
	v_mfma_f32_16x16x32_bf16 v[12:15], v[156:159], v[196:199], v[12:15]
	v_mfma_f32_16x16x32_bf16 v[8:11], v[164:167], v[196:199], v[8:11]
	s_setprio 0
	s_barrier
	s_add_u32 s28, s34, 0x80080
	s_addc_u32 s29, s35, 0
	s_add_i32 s34, s84, s42
	s_mov_b32 m0, s34
	s_nop 0
	global_load_lds_dwordx4 v130, s[28:29]
	s_add_i32 m0, s34, 0x2000
	s_nop 0
	global_load_lds_dwordx4 v134, s[28:29]
	s_waitcnt vmcnt(6)
	s_barrier
	s_setprio 1
	v_mfma_f32_16x16x32_bf16 v[52:55], v[202:205], v[168:171], v[52:55]
	v_mfma_f32_16x16x32_bf16 v[48:51], v[210:213], v[168:171], v[48:51]
	v_mfma_f32_16x16x32_bf16 v[36:39], v[202:205], v[176:179], v[36:39]
	v_mfma_f32_16x16x32_bf16 v[32:35], v[210:213], v[176:179], v[32:35]
	v_mfma_f32_16x16x32_bf16 v[20:23], v[202:205], v[184:187], v[20:23]
	v_mfma_f32_16x16x32_bf16 v[16:19], v[210:213], v[184:187], v[16:19]
	v_mfma_f32_16x16x32_bf16 v[4:7], v[202:205], v[192:195], v[4:7]
	v_mfma_f32_16x16x32_bf16 v[0:3], v[210:213], v[192:195], v[0:3]
	v_mfma_f32_16x16x32_bf16 v[52:55], v[206:209], v[172:175], v[52:55]
	v_mfma_f32_16x16x32_bf16 v[48:51], v[214:217], v[172:175], v[48:51]
	v_mfma_f32_16x16x32_bf16 v[36:39], v[206:209], v[180:183], v[36:39]
	v_mfma_f32_16x16x32_bf16 v[32:35], v[214:217], v[180:183], v[32:35]
	v_mfma_f32_16x16x32_bf16 v[20:23], v[206:209], v[188:191], v[20:23]
	v_mfma_f32_16x16x32_bf16 v[16:19], v[214:217], v[188:191], v[16:19]
	v_mfma_f32_16x16x32_bf16 v[4:7], v[206:209], v[196:199], v[4:7]
	v_mfma_f32_16x16x32_bf16 v[0:3], v[214:217], v[196:199], v[0:3]
	s_setprio 0
	s_add_i32 s56, s56, 2
	s_add_u32 s30, s30, 0x100
	s_addc_u32 s31, s31, 0
	s_add_u32 s54, s54, 0x100
	s_addc_u32 s55, s55, 0
	s_cmp_gt_u32 s56, 29
	s_barrier
	s_cbranch_scc0 .LBB0_591
	v_lshl_add_u32 v152, s26, 8, v146
	v_lshl_or_b32 v144, s51, 8, v148
	v_ashrrev_i32_e32 v153, 31, v152
	v_ashrrev_i32_e32 v145, 31, v144
	v_lshlrev_b64 v[154:155], 14, v[152:153]
	v_lshl_add_u64 v[154:155], s[88:89], 0, v[154:155]
	v_lshlrev_b64 v[156:157], 1, v[144:145]
	v_max_f32_e32 v120, 0, v120
	v_max_f32_e32 v121, 0, v121
	v_lshl_add_u64 v[144:145], v[154:155], 0, v[156:157]
	v_pk_mul_f32 v[154:155], v[120:121], v[120:121]
	v_max_f32_e32 v121, v122, v122
	v_max_f32_e32 v120, v126, v126
	v_max_f32_e32 v122, 0, v121
	v_max_f32_e32 v121, v127, v127
	v_max_f32_e32 v124, 0, v124
	v_max_f32_e32 v125, 0, v125
	v_max_f32_e32 v120, 0, v120
	v_max_f32_e32 v121, 0, v121
	v_max_f32_e32 v123, 0, v123
	v_pk_mul_f32 v[124:125], v[124:125], v[124:125]
	v_pk_mul_f32 v[126:127], v[120:121], v[120:121]
	v_pk_mul_f32 v[158:159], v[122:123], v[122:123]
	v_cvt_pk_bf16_f32 v120, v124, v125
	v_cvt_pk_bf16_f32 v121, v126, v127
	v_cvt_pk_bf16_f32 v122, v154, v155
	v_cvt_pk_bf16_f32 v123, v158, v159
	v_max_f32_e32 v112, 0, v112
	v_max_f32_e32 v113, 0, v113
	global_store_dwordx4 v[144:145], v[120:123], off sc1
	s_nop 1
	v_pk_mul_f32 v[120:121], v[112:113], v[112:113]
	v_max_f32_e32 v113, v114, v114
	v_max_f32_e32 v112, v118, v118
	v_max_f32_e32 v114, 0, v113
	v_max_f32_e32 v113, v119, v119
	v_max_f32_e32 v116, 0, v116
	v_max_f32_e32 v117, 0, v117
	v_max_f32_e32 v112, 0, v112
	v_max_f32_e32 v113, 0, v113
	v_max_f32_e32 v115, 0, v115
	v_pk_mul_f32 v[116:117], v[116:117], v[116:117]
	v_pk_mul_f32 v[118:119], v[112:113], v[112:113]
	v_pk_mul_f32 v[122:123], v[114:115], v[114:115]
	v_cvt_pk_bf16_f32 v112, v116, v117
	v_cvt_pk_bf16_f32 v113, v118, v119
	v_cvt_pk_bf16_f32 v114, v120, v121
	v_cvt_pk_bf16_f32 v115, v122, v123
	v_max_f32_e32 v104, 0, v104
	v_max_f32_e32 v105, 0, v105
	global_store_dwordx4 v[144:145], v[112:115], off offset:256 sc1
	s_nop 1
	v_or_b32_e32 v112, 16, v152
	v_pk_mul_f32 v[114:115], v[104:105], v[104:105]
	v_max_f32_e32 v105, v106, v106
	v_ashrrev_i32_e32 v113, 31, v112
	v_max_f32_e32 v104, v110, v110
	v_max_f32_e32 v106, 0, v105
	v_max_f32_e32 v105, v111, v111
	v_lshlrev_b64 v[112:113], 14, v[112:113]
	v_max_f32_e32 v108, 0, v108
	v_max_f32_e32 v109, 0, v109
	v_max_f32_e32 v104, 0, v104
	v_max_f32_e32 v105, 0, v105
	v_max_f32_e32 v107, 0, v107
	v_lshl_add_u64 v[112:113], s[88:89], 0, v[112:113]
	v_pk_mul_f32 v[108:109], v[108:109], v[108:109]
	v_pk_mul_f32 v[110:111], v[104:105], v[104:105]
	v_pk_mul_f32 v[116:117], v[106:107], v[106:107]
	v_lshl_add_u64 v[112:113], v[112:113], 0, v[156:157]
	v_cvt_pk_bf16_f32 v104, v108, v109
	v_cvt_pk_bf16_f32 v105, v110, v111
	v_cvt_pk_bf16_f32 v106, v114, v115
	v_cvt_pk_bf16_f32 v107, v116, v117
	v_max_f32_e32 v96, 0, v96
	v_max_f32_e32 v97, 0, v97
	global_store_dwordx4 v[112:113], v[104:107], off sc1
	s_nop 1
	v_pk_mul_f32 v[104:105], v[96:97], v[96:97]
	v_max_f32_e32 v97, v98, v98
	v_max_f32_e32 v96, v102, v102
; __device__ __forceinline__ unsigned cvt_pk_bf16(float lo, float hi) { const bf16x2_t r = __builtin_convertvector((f32x2){lo, hi}, bf16x2_t); return __builtin_bit_cast(unsigned, r); }
;     __device__ __forceinline__ void operator()(const AccT& acc, const Unit& u, int wr, int wc, int fr, int fq) const {
;     ...
;         for (int ai = 0; ai < 2; ++ai)
; #pragma unroll
;             for (int m = 0; m < 4; ++m) { bf16_t* rowp = O + (size_t)(row0 + ai * HALF + m * 16) * DFF + col0;
; #pragma unroll
;                 for (int bj = 0; bj < 2; ++bj) { f32x4 v0 = acc[ai][bj][m][0], v1 = acc[ai][bj][m][1];
; #pragma unroll
;                     for (int j = 0; j < 4; ++j) { float a = fmaxf(v0[j], 0.f), b = fmaxf(v1[j], 0.f); v0[j] = a * a; v1[j] = b * b; }
;                     u32x4 w; w.x = cvt_pk_bf16(v0[0], v0[1]); w.y = cvt_pk_bf16(v0[2], v0[3]); w.z = cvt_pk_bf16(v1[0], v1[1]); w.w = cvt_pk_bf16(v1[2], v1[3]);
;                     *(u32x4*)(rowp + bj * HALF) = w; } }
	v_max_f32_e32 v98, 0, v97
	v_max_f32_e32 v97, v103, v103
	v_max_f32_e32 v100, 0, v100
	v_max_f32_e32 v101, 0, v101
	v_max_f32_e32 v96, 0, v96
	v_max_f32_e32 v97, 0, v97
	v_max_f32_e32 v99, 0, v99
	v_pk_mul_f32 v[100:101], v[100:101], v[100:101]
	v_pk_mul_f32 v[102:103], v[96:97], v[96:97]
	v_pk_mul_f32 v[106:107], v[98:99], v[98:99]
	v_cvt_pk_bf16_f32 v96, v100, v101
	v_cvt_pk_bf16_f32 v97, v102, v103
	v_cvt_pk_bf16_f32 v98, v104, v105
	v_cvt_pk_bf16_f32 v99, v106, v107
	v_max_f32_e32 v88, 0, v88
	v_max_f32_e32 v89, 0, v89
	global_store_dwordx4 v[112:113], v[96:99], off offset:256 sc1
	s_nop 1
	v_or_b32_e32 v96, 32, v152
	v_pk_mul_f32 v[98:99], v[88:89], v[88:89]
	v_max_f32_e32 v89, v90, v90
	v_ashrrev_i32_e32 v97, 31, v96
	v_max_f32_e32 v88, v94, v94
	v_max_f32_e32 v90, 0, v89
	v_max_f32_e32 v89, v95, v95
	v_lshlrev_b64 v[96:97], 14, v[96:97]
	v_max_f32_e32 v92, 0, v92
	v_max_f32_e32 v93, 0, v93
	v_max_f32_e32 v88, 0, v88
	v_max_f32_e32 v89, 0, v89
	v_max_f32_e32 v91, 0, v91
	v_lshl_add_u64 v[96:97], s[88:89], 0, v[96:97]
	v_pk_mul_f32 v[92:93], v[92:93], v[92:93]
	v_pk_mul_f32 v[94:95], v[88:89], v[88:89]
	v_pk_mul_f32 v[100:101], v[90:91], v[90:91]
	v_lshl_add_u64 v[96:97], v[96:97], 0, v[156:157]
	v_cvt_pk_bf16_f32 v88, v92, v93
	v_cvt_pk_bf16_f32 v89, v94, v95
	v_cvt_pk_bf16_f32 v90, v98, v99
	v_cvt_pk_bf16_f32 v91, v100, v101
	v_max_f32_e32 v80, 0, v80
	v_max_f32_e32 v81, 0, v81
	global_store_dwordx4 v[96:97], v[88:91], off sc1
	s_nop 1
	v_pk_mul_f32 v[88:89], v[80:81], v[80:81]
	v_max_f32_e32 v81, v82, v82
	v_max_f32_e32 v80, v86, v86
	v_max_f32_e32 v82, 0, v81
	v_max_f32_e32 v81, v87, v87
	v_max_f32_e32 v84, 0, v84
	v_max_f32_e32 v85, 0, v85
	v_max_f32_e32 v80, 0, v80
	v_max_f32_e32 v81, 0, v81
	v_max_f32_e32 v83, 0, v83
	v_pk_mul_f32 v[84:85], v[84:85], v[84:85]
	v_pk_mul_f32 v[86:87], v[80:81], v[80:81]
	v_pk_mul_f32 v[90:91], v[82:83], v[82:83]
	v_cvt_pk_bf16_f32 v80, v84, v85
	v_cvt_pk_bf16_f32 v81, v86, v87
	v_cvt_pk_bf16_f32 v82, v88, v89
	v_cvt_pk_bf16_f32 v83, v90, v91
	v_max_f32_e32 v72, 0, v72
	v_max_f32_e32 v73, 0, v73
	global_store_dwordx4 v[96:97], v[80:83], off offset:256 sc1
	s_nop 1
	v_or_b32_e32 v80, 48, v152
	v_pk_mul_f32 v[82:83], v[72:73], v[72:73]
	v_max_f32_e32 v73, v74, v74
	v_ashrrev_i32_e32 v81, 31, v80
	v_max_f32_e32 v72, v78, v78
	v_max_f32_e32 v74, 0, v73
	v_max_f32_e32 v73, v79, v79
	v_lshlrev_b64 v[80:81], 14, v[80:81]
	v_max_f32_e32 v76, 0, v76
	v_max_f32_e32 v77, 0, v77
	v_max_f32_e32 v72, 0, v72
	v_max_f32_e32 v73, 0, v73
	v_max_f32_e32 v75, 0, v75
	v_lshl_add_u64 v[80:81], s[88:89], 0, v[80:81]
	v_pk_mul_f32 v[76:77], v[76:77], v[76:77]
	v_pk_mul_f32 v[78:79], v[72:73], v[72:73]
	v_pk_mul_f32 v[84:85], v[74:75], v[74:75]
	v_lshl_add_u64 v[80:81], v[80:81], 0, v[156:157]
	v_cvt_pk_bf16_f32 v72, v76, v77
	v_cvt_pk_bf16_f32 v73, v78, v79
	v_cvt_pk_bf16_f32 v74, v82, v83
	v_cvt_pk_bf16_f32 v75, v84, v85
	v_max_f32_e32 v64, 0, v64
	v_max_f32_e32 v65, 0, v65
	global_store_dwordx4 v[80:81], v[72:75], off sc1
	s_nop 1
	v_pk_mul_f32 v[72:73], v[64:65], v[64:65]
	v_max_f32_e32 v65, v66, v66
	v_max_f32_e32 v64, v70, v70
	v_max_f32_e32 v66, 0, v65
	v_max_f32_e32 v65, v71, v71
	v_max_f32_e32 v68, 0, v68
	v_max_f32_e32 v69, 0, v69
	v_max_f32_e32 v64, 0, v64
	v_max_f32_e32 v65, 0, v65
	v_max_f32_e32 v67, 0, v67
	v_pk_mul_f32 v[68:69], v[68:69], v[68:69]
	v_pk_mul_f32 v[70:71], v[64:65], v[64:65]
	v_pk_mul_f32 v[74:75], v[66:67], v[66:67]
	v_cvt_pk_bf16_f32 v64, v68, v69
	v_cvt_pk_bf16_f32 v65, v70, v71
	v_cvt_pk_bf16_f32 v66, v72, v73
	v_cvt_pk_bf16_f32 v67, v74, v75
	v_max_f32_e32 v56, 0, v56
	v_max_f32_e32 v57, 0, v57
	global_store_dwordx4 v[80:81], v[64:67], off offset:256 sc1
	s_nop 1
	v_pk_mul_f32 v[66:67], v[56:57], v[56:57]
	v_max_f32_e32 v57, v58, v58
	v_max_f32_e32 v60, 0, v60
	v_max_f32_e32 v61, 0, v61
	v_max_f32_e32 v56, v62, v62
	v_max_f32_e32 v58, 0, v57
	v_max_f32_e32 v57, v63, v63
	v_pk_mul_f32 v[60:61], v[60:61], v[60:61]
	v_max_f32_e32 v56, 0, v56
	v_max_f32_e32 v57, 0, v57
	v_max_f32_e32 v59, 0, v59
	s_mov_b32 s5, 0x200000
	v_pk_mul_f32 v[62:63], v[56:57], v[56:57]
	v_pk_mul_f32 v[68:69], v[58:59], v[58:59]
	v_cvt_pk_bf16_f32 v56, v60, v61
	v_add_co_u32_e32 v60, vcc, s5, v144
	v_cvt_pk_bf16_f32 v57, v62, v63
	v_cvt_pk_bf16_f32 v58, v66, v67
	v_cvt_pk_bf16_f32 v59, v68, v69
	v_addc_co_u32_e32 v61, vcc, 0, v145, vcc
	v_max_f32_e32 v48, 0, v48
	v_max_f32_e32 v49, 0, v49
	global_store_dwordx4 v[60:61], v[56:59], off sc1
	s_nop 1
	v_pk_mul_f32 v[56:57], v[48:49], v[48:49]
	v_max_f32_e32 v49, v50, v50
	v_max_f32_e32 v48, v54, v54
	v_max_f32_e32 v50, 0, v49
	v_max_f32_e32 v49, v55, v55
	v_max_f32_e32 v52, 0, v52
	v_max_f32_e32 v53, 0, v53
	v_max_f32_e32 v48, 0, v48
	v_max_f32_e32 v49, 0, v49
	v_max_f32_e32 v51, 0, v51
	s_mov_b64 s[28:29], 0x200000
	v_pk_mul_f32 v[52:53], v[52:53], v[52:53]
	v_pk_mul_f32 v[54:55], v[48:49], v[48:49]
	v_pk_mul_f32 v[58:59], v[50:51], v[50:51]
; __device__ __forceinline__ unsigned cvt_pk_bf16(float lo, float hi) { const bf16x2_t r = __builtin_convertvector((f32x2){lo, hi}, bf16x2_t); return __builtin_bit_cast(unsigned, r); }
; #define PG8_WAIT_V(n) asm volatile("s_waitcnt vmcnt(" #n ")" ::: "memory")
; #define PG8_BAR __builtin_amdgcn_s_barrier()
; template <class Epi>
; __device__ __forceinline__ void gemm_phase(LAS unsigned char* lds, const bf16_t* A, int lda, const bf16_t* Bt, int ldb, int M, int N, int K, int asel, const Epi& E, const int fixed_round = -1) {
;     ...
;         if (!has_next) break;
; #pragma unroll
;         for (int a = 0; a < 2; ++a)
; #pragma unroll
;             for (int b = 0; b < 2; ++b)
; #pragma unroll
;                 for (int m = 0; m < 4; ++m)
; #pragma unroll
;                     for (int n = 0; n < 2; ++n) acc[a][b][m][n] = (f32x4){0.f, 0.f, 0.f, 0.f};
;         cur = nxt; cA = nA; cB = nB; ++ui;
;     }
;     PG8_WAIT_V(0);
;     if (wr == 0) PG8_BAR;
;     PG8_BAR;
;     __device__ __forceinline__ void operator()(const AccT& acc, const Unit& u, int wr, int wc, int fr, int fq) const {
;     ...
;         for (int ai = 0; ai < 2; ++ai)
; #pragma unroll
;             for (int m = 0; m < 4; ++m) { bf16_t* rowp = O + (size_t)(row0 + ai * HALF + m * 16) * DFF + col0;
; #pragma unroll
;                 for (int bj = 0; bj < 2; ++bj) { f32x4 v0 = acc[ai][bj][m][0], v1 = acc[ai][bj][m][1];
; #pragma unroll
;                     for (int j = 0; j < 4; ++j) { float a = fmaxf(v0[j], 0.f), b = fmaxf(v1[j], 0.f); v0[j] = a * a; v1[j] = b * b; }
;                     u32x4 w; w.x = cvt_pk_bf16(v0[0], v0[1]); w.y = cvt_pk_bf16(v0[2], v0[3]); w.z = cvt_pk_bf16(v1[0], v1[1]); w.w = cvt_pk_bf16(v1[2], v1[3]);
;                     *(u32x4*)(rowp + bj * HALF) = w; } }
;     }
	v_lshl_add_u64 v[64:65], v[144:145], 0, s[28:29]
	v_cvt_pk_bf16_f32 v48, v52, v53
	v_cvt_pk_bf16_f32 v49, v54, v55
	v_cvt_pk_bf16_f32 v50, v56, v57
	v_cvt_pk_bf16_f32 v51, v58, v59
	v_max_f32_e32 v40, 0, v40
	v_max_f32_e32 v41, 0, v41
	global_store_dwordx4 v[64:65], v[48:51], off offset:256 sc1
	s_nop 1
	v_pk_mul_f32 v[50:51], v[40:41], v[40:41]
	v_max_f32_e32 v41, v42, v42
	v_max_f32_e32 v44, 0, v44
	v_max_f32_e32 v45, 0, v45
	v_max_f32_e32 v40, v46, v46
	v_max_f32_e32 v42, 0, v41
	v_max_f32_e32 v41, v47, v47
	v_pk_mul_f32 v[44:45], v[44:45], v[44:45]
	v_max_f32_e32 v40, 0, v40
	v_max_f32_e32 v41, 0, v41
	v_max_f32_e32 v43, 0, v43
	s_mov_b32 s5, 0x240000
	v_pk_mul_f32 v[46:47], v[40:41], v[40:41]
	v_pk_mul_f32 v[52:53], v[42:43], v[42:43]
	v_cvt_pk_bf16_f32 v40, v44, v45
	v_add_co_u32_e32 v44, vcc, s5, v144
	v_cvt_pk_bf16_f32 v41, v46, v47
	v_cvt_pk_bf16_f32 v42, v50, v51
	v_cvt_pk_bf16_f32 v43, v52, v53
	v_addc_co_u32_e32 v45, vcc, 0, v145, vcc
	v_max_f32_e32 v32, 0, v32
	v_max_f32_e32 v33, 0, v33
	global_store_dwordx4 v[44:45], v[40:43], off sc1
	s_nop 1
	v_pk_mul_f32 v[40:41], v[32:33], v[32:33]
	v_max_f32_e32 v33, v34, v34
	v_max_f32_e32 v32, v38, v38
	v_max_f32_e32 v34, 0, v33
	v_max_f32_e32 v33, v39, v39
	v_max_f32_e32 v36, 0, v36
	v_max_f32_e32 v37, 0, v37
	v_max_f32_e32 v32, 0, v32
	v_max_f32_e32 v33, 0, v33
	v_max_f32_e32 v35, 0, v35
	s_mov_b64 s[28:29], 0x240000
	v_pk_mul_f32 v[36:37], v[36:37], v[36:37]
	v_pk_mul_f32 v[38:39], v[32:33], v[32:33]
	v_pk_mul_f32 v[42:43], v[34:35], v[34:35]
	v_lshl_add_u64 v[48:49], v[144:145], 0, s[28:29]
	v_cvt_pk_bf16_f32 v32, v36, v37
	v_cvt_pk_bf16_f32 v33, v38, v39
	v_cvt_pk_bf16_f32 v34, v40, v41
	v_cvt_pk_bf16_f32 v35, v42, v43
	v_max_f32_e32 v24, 0, v24
	v_max_f32_e32 v25, 0, v25
	global_store_dwordx4 v[48:49], v[32:35], off offset:256 sc1
	s_nop 1
	v_pk_mul_f32 v[34:35], v[24:25], v[24:25]
	v_max_f32_e32 v25, v26, v26
	v_max_f32_e32 v28, 0, v28
	v_max_f32_e32 v29, 0, v29
	v_max_f32_e32 v24, v30, v30
	v_max_f32_e32 v26, 0, v25
	v_max_f32_e32 v25, v31, v31
	v_pk_mul_f32 v[28:29], v[28:29], v[28:29]
	v_max_f32_e32 v24, 0, v24
	v_max_f32_e32 v25, 0, v25
	v_max_f32_e32 v27, 0, v27
	s_mov_b32 s5, 0x280000
	v_pk_mul_f32 v[30:31], v[24:25], v[24:25]
	v_pk_mul_f32 v[36:37], v[26:27], v[26:27]
	v_cvt_pk_bf16_f32 v24, v28, v29
	v_add_co_u32_e32 v28, vcc, s5, v144
	v_cvt_pk_bf16_f32 v25, v30, v31
	v_cvt_pk_bf16_f32 v26, v34, v35
	v_cvt_pk_bf16_f32 v27, v36, v37
	v_addc_co_u32_e32 v29, vcc, 0, v145, vcc
	v_max_f32_e32 v16, 0, v16
	v_max_f32_e32 v17, 0, v17
	global_store_dwordx4 v[28:29], v[24:27], off sc1
	s_nop 1
	v_pk_mul_f32 v[24:25], v[16:17], v[16:17]
	v_max_f32_e32 v17, v18, v18
	v_max_f32_e32 v16, v22, v22
	v_max_f32_e32 v18, 0, v17
	v_max_f32_e32 v17, v23, v23
	v_max_f32_e32 v20, 0, v20
	v_max_f32_e32 v21, 0, v21
	v_max_f32_e32 v16, 0, v16
	v_max_f32_e32 v17, 0, v17
	v_max_f32_e32 v19, 0, v19
	s_mov_b64 s[28:29], 0x280000
	v_pk_mul_f32 v[20:21], v[20:21], v[20:21]
	v_pk_mul_f32 v[22:23], v[16:17], v[16:17]
	v_pk_mul_f32 v[26:27], v[18:19], v[18:19]
	v_lshl_add_u64 v[32:33], v[144:145], 0, s[28:29]
	v_cvt_pk_bf16_f32 v16, v20, v21
	v_cvt_pk_bf16_f32 v17, v22, v23
	v_cvt_pk_bf16_f32 v18, v24, v25
	v_cvt_pk_bf16_f32 v19, v26, v27
	v_max_f32_e32 v8, 0, v8
	v_max_f32_e32 v9, 0, v9
	global_store_dwordx4 v[32:33], v[16:19], off offset:256 sc1
	s_nop 1
	v_pk_mul_f32 v[18:19], v[8:9], v[8:9]
	v_max_f32_e32 v9, v10, v10
	v_max_f32_e32 v12, 0, v12
	v_max_f32_e32 v13, 0, v13
	v_max_f32_e32 v8, v14, v14
	v_max_f32_e32 v10, 0, v9
	v_max_f32_e32 v9, v15, v15
	v_pk_mul_f32 v[12:13], v[12:13], v[12:13]
	v_max_f32_e32 v8, 0, v8
	v_max_f32_e32 v9, 0, v9
	v_max_f32_e32 v11, 0, v11
	v_pk_mul_f32 v[14:15], v[8:9], v[8:9]
	v_pk_mul_f32 v[20:21], v[10:11], v[10:11]
	v_cvt_pk_bf16_f32 v8, v12, v13
	v_add_co_u32_e32 v12, vcc, s50, v144
	v_cvt_pk_bf16_f32 v9, v14, v15
	v_cvt_pk_bf16_f32 v10, v18, v19
	v_cvt_pk_bf16_f32 v11, v20, v21
	v_addc_co_u32_e32 v13, vcc, 0, v145, vcc
	v_max_f32_e32 v0, 0, v0
	v_max_f32_e32 v1, 0, v1
	global_store_dwordx4 v[12:13], v[8:11], off sc1
	s_nop 1
	v_pk_mul_f32 v[8:9], v[0:1], v[0:1]
	v_max_f32_e32 v1, v2, v2
	v_max_f32_e32 v0, v6, v6
	v_max_f32_e32 v2, 0, v1
	v_max_f32_e32 v1, v7, v7
	v_max_f32_e32 v4, 0, v4
	v_max_f32_e32 v5, 0, v5
	v_max_f32_e32 v0, 0, v0
	v_max_f32_e32 v1, 0, v1
	v_max_f32_e32 v3, 0, v3
	s_mov_b64 s[28:29], 0x2c0000
	v_pk_mul_f32 v[4:5], v[4:5], v[4:5]
	v_pk_mul_f32 v[6:7], v[0:1], v[0:1]
	v_pk_mul_f32 v[10:11], v[2:3], v[2:3]
	v_lshl_add_u64 v[16:17], v[144:145], 0, s[28:29]
	v_cvt_pk_bf16_f32 v0, v4, v5
	v_cvt_pk_bf16_f32 v1, v6, v7
	v_cvt_pk_bf16_f32 v2, v8, v9
	v_cvt_pk_bf16_f32 v3, v10, v11
	s_and_b64 vcc, exec, s[0:1]
	s_mov_b32 s51, s4
	s_mov_b32 s26, s6
	s_mov_b64 s[34:35], s[20:21]
	s_mov_b64 s[30:31], s[18:19]
	global_store_dwordx4 v[16:17], v[0:3], off offset:256 sc1
	s_cbranch_vccz .LBB0_584
	s_waitcnt vmcnt(0)
	s_cmpk_gt_u32 s33, 0xff
	s_cbranch_scc1 .LBB0_595
	s_barrier

; #define PG8_STAGE(bufoff, gbase, voff) do { _Pragma("unroll") for (int _i = 0; _i < 2; ++_i) \
;         __builtin_amdgcn_global_load_lds((const unsigned*)((const char*)(gbase) + (voff)[_i]), (LAS unsigned*)(lds + (bufoff) + ldsw + _i * 8192), 16, 0, 0); } while (0)
; #define PG8_LDA(dst, b, h) do { _Pragma("unroll") for (int m = 0; m < 4; ++m) _Pragma("unroll") for (int k = 0; k < 2; ++k) dst[m][k] = *(const LAS bf16x8*)(lds + PG8_SA(b, h) + aoff + m * 2048 + k * 1024); } while (0)
; #define PG8_WAIT_V(n) asm volatile("s_waitcnt vmcnt(" #n ")" ::: "memory")
; template <class Epi>
; __device__ __forceinline__ void gemm_phase(LAS unsigned char* lds, const bf16_t* A, int lda, const bf16_t* Bt, int ldb, int M, int N, int K, int asel, const Epi& E, const int fixed_round = -1) {
;     ...
;         for (int t = 0; t < nt; t += 2) {
;             const bool last = (t == nt - 2);
;             const char* a1 = cA + (size_t)(t + 1) * kstep;
;             const char* a2 = last ? nA : cA + (size_t)(t + 2) * kstep; const char* b2 = last ? nB : cB + (size_t)(t + 2) * kstep;
;             const char* a3 = a2 + kstep; const char* b3 = b2 + kstep;
;             PG8_LDB(B0, 0, 0); PG8_SCHED; PG8_LDA(At, 0, 0); PG8_STAGE(PG8_SA(1, 1), a1 + hstepA, voffA);
;             PG8_WAIT_L(8); PG8_BAR; PG8_WAIT_L(0); PG8_MMA(0, 0, At, B0); PG8_BAR; PG8_SCHED;
;             PG8_LDB(B1, 0, 1); PG8_STAGE(PG8_SB(0, 0), b2, voffB);
;             PG8_BAR; PG8_WAIT_L(0); PG8_MMA(0, 1, At, B1); PG8_BAR;
;             PG8_LDA(At, 0, 1); PG8_STAGE(PG8_SA(0, 0), a2, voffA);
;             PG8_BAR; PG8_WAIT_L(0); PG8_MMA(1, 0, At, B0); PG8_BAR; PG8_SCHED;
;             PG8_STAGE(PG8_SB(0, 1), b2 + hstepB, voffB);
;             PG8_WAIT_V(6); PG8_BAR; PG8_MMA(1, 1, At, B1); PG8_BAR;
;             PG8_LDB(B0, 1, 0); PG8_SCHED; PG8_LDA(At, 1, 0); PG8_STAGE(PG8_SA(0, 1), a2 + hstepA, voffA);
;             PG8_WAIT_L(8); PG8_BAR; PG8_WAIT_L(0); PG8_MMA(0, 0, At, B0); PG8_BAR; PG8_SCHED;
;             PG8_LDB(B1, 1, 1); PG8_STAGE(PG8_SB(1, 0), b3, voffB);
;             PG8_BAR; PG8_WAIT_L(0); PG8_MMA(0, 1, At, B1); PG8_BAR;
;             PG8_LDA(At, 1, 1); PG8_STAGE(PG8_SA(1, 0), a3, voffA);
;             PG8_BAR; PG8_WAIT_L(0); PG8_MMA(1, 0, At, B0); PG8_BAR; PG8_SCHED;
;             PG8_STAGE(PG8_SB(1, 1), b3 + hstepB, voffB);
;             PG8_WAIT_V(6); PG8_BAR; PG8_MMA(1, 1, At, B1); PG8_BAR;
.LBB0_1223:
	ds_read_b128 v[152:155], v149
	ds_read_b128 v[156:159], v149 offset:1024
	ds_read_b128 v[160:163], v149 offset:2048
	ds_read_b128 v[164:167], v149 offset:3072
	s_add_u32 s48, s46, 0xfff80080
	s_addc_u32 s49, s47, -1
	s_cmp_eq_u32 s70, 28
	s_cselect_b32 s51, s29, s49
	s_cselect_b32 s50, s66, s48
	s_cselect_b32 s49, s25, s69
	s_cselect_b32 s48, s67, s68
	s_add_i32 m0, s45, 0xc000
	ds_read_b128 v[168:171], v150
	ds_read_b128 v[172:175], v150 offset:1024
	ds_read_b128 v[176:179], v150 offset:2048
	ds_read_b128 v[180:183], v150 offset:3072
	ds_read_b128 v[184:187], v150 offset:4096
	ds_read_b128 v[188:191], v150 offset:5120
	ds_read_b128 v[192:195], v150 offset:6144
	ds_read_b128 v[196:199], v150 offset:7168
	global_load_lds_dwordx4 v136, s[46:47]
	s_add_i32 m0, s45, 0xe000
	s_nop 0
	global_load_lds_dwordx4 v138, s[46:47]
	s_waitcnt lgkmcnt(8)
	s_barrier
	s_waitcnt lgkmcnt(0)
	s_setprio 1
	s_waitcnt lgkmcnt(0)
	v_mfma_f32_16x16x32_bf16 v[124:127], v[152:155], v[168:171], v[124:127]
	v_mfma_f32_16x16x32_bf16 v[120:123], v[160:163], v[168:171], v[120:123]
	v_mfma_f32_16x16x32_bf16 v[108:111], v[152:155], v[176:179], v[108:111]
	v_mfma_f32_16x16x32_bf16 v[104:107], v[160:163], v[176:179], v[104:107]
	v_mfma_f32_16x16x32_bf16 v[92:95], v[152:155], v[184:187], v[92:95]
	v_mfma_f32_16x16x32_bf16 v[88:91], v[160:163], v[184:187], v[88:91]
	v_mfma_f32_16x16x32_bf16 v[76:79], v[152:155], v[192:195], v[76:79]
	v_mfma_f32_16x16x32_bf16 v[72:75], v[160:163], v[192:195], v[72:75]
	v_mfma_f32_16x16x32_bf16 v[124:127], v[156:159], v[172:175], v[124:127]
	v_mfma_f32_16x16x32_bf16 v[120:123], v[164:167], v[172:175], v[120:123]
	v_mfma_f32_16x16x32_bf16 v[108:111], v[156:159], v[180:183], v[108:111]
	v_mfma_f32_16x16x32_bf16 v[104:107], v[164:167], v[180:183], v[104:107]
	v_mfma_f32_16x16x32_bf16 v[92:95], v[156:159], v[188:191], v[92:95]
	v_mfma_f32_16x16x32_bf16 v[88:91], v[164:167], v[188:191], v[88:91]
	v_mfma_f32_16x16x32_bf16 v[76:79], v[156:159], v[196:199], v[76:79]
	v_mfma_f32_16x16x32_bf16 v[72:75], v[164:167], v[196:199], v[72:75]
	s_setprio 0
	s_barrier
	s_add_i32 s71, s81, s54
	s_add_u32 s98, s48, s2
	s_addc_u32 s99, s49, s3
	s_mov_b32 m0, s71
	ds_read_b128 v[202:205], v151
	ds_read_b128 v[206:209], v151 offset:1024
	ds_read_b128 v[210:213], v151 offset:2048
	ds_read_b128 v[214:217], v151 offset:3072
	global_load_lds_dwordx4 v130, s[48:49]
	s_add_i32 m0, s71, 0x2000
	s_nop 0
	global_load_lds_dwordx4 v134, s[48:49]
	s_barrier
	s_waitcnt lgkmcnt(0)
	s_setprio 1
	s_waitcnt lgkmcnt(0)
	v_mfma_f32_16x16x32_bf16 v[116:119], v[202:205], v[168:171], v[116:119]
	v_mfma_f32_16x16x32_bf16 v[112:115], v[210:213], v[168:171], v[112:115]
	v_mfma_f32_16x16x32_bf16 v[100:103], v[202:205], v[176:179], v[100:103]
	v_mfma_f32_16x16x32_bf16 v[96:99], v[210:213], v[176:179], v[96:99]
	v_mfma_f32_16x16x32_bf16 v[84:87], v[202:205], v[184:187], v[84:87]
	v_mfma_f32_16x16x32_bf16 v[80:83], v[210:213], v[184:187], v[80:83]
	v_mfma_f32_16x16x32_bf16 v[68:71], v[202:205], v[192:195], v[68:71]
	v_mfma_f32_16x16x32_bf16 v[64:67], v[210:213], v[192:195], v[64:67]
	v_mfma_f32_16x16x32_bf16 v[116:119], v[206:209], v[172:175], v[116:119]
	v_mfma_f32_16x16x32_bf16 v[112:115], v[214:217], v[172:175], v[112:115]
	v_mfma_f32_16x16x32_bf16 v[100:103], v[206:209], v[180:183], v[100:103]
	v_mfma_f32_16x16x32_bf16 v[96:99], v[214:217], v[180:183], v[96:99]
	v_mfma_f32_16x16x32_bf16 v[84:87], v[206:209], v[188:191], v[84:87]
	v_mfma_f32_16x16x32_bf16 v[80:83], v[214:217], v[188:191], v[80:83]
	v_mfma_f32_16x16x32_bf16 v[68:71], v[206:209], v[196:199], v[68:71]
	v_mfma_f32_16x16x32_bf16 v[64:67], v[214:217], v[196:199], v[64:67]
	s_setprio 0
	s_mov_b32 m0, s45
	s_add_u32 s100, s50, s2
	s_addc_u32 s101, s51, s3
	s_barrier
	ds_read_b128 v[168:171], v150 offset:16384
	ds_read_b128 v[172:175], v150 offset:17408
	ds_read_b128 v[176:179], v150 offset:18432
	ds_read_b128 v[180:183], v150 offset:19456
	ds_read_b128 v[184:187], v150 offset:20480
	ds_read_b128 v[188:191], v150 offset:21504
	ds_read_b128 v[192:195], v150 offset:22528
	ds_read_b128 v[196:199], v150 offset:23552
	global_load_lds_dwordx4 v128, s[50:51]
	s_mov_b32 m0, s55
	s_nop 0
	global_load_lds_dwordx4 v132, s[50:51]
	s_barrier
	s_waitcnt lgkmcnt(0)
	s_setprio 1
	s_waitcnt lgkmcnt(0)
	v_mfma_f32_16x16x32_bf16 v[60:63], v[152:155], v[168:171], v[60:63]
	v_mfma_f32_16x16x32_bf16 v[56:59], v[160:163], v[168:171], v[56:59]
	v_mfma_f32_16x16x32_bf16 v[44:47], v[152:155], v[176:179], v[44:47]
	v_mfma_f32_16x16x32_bf16 v[40:43], v[160:163], v[176:179], v[40:43]
	v_mfma_f32_16x16x32_bf16 v[28:31], v[152:155], v[184:187], v[28:31]
	v_mfma_f32_16x16x32_bf16 v[24:27], v[160:163], v[184:187], v[24:27]
	v_mfma_f32_16x16x32_bf16 v[12:15], v[152:155], v[192:195], v[12:15]
	v_mfma_f32_16x16x32_bf16 v[8:11], v[160:163], v[192:195], v[8:11]
	v_mfma_f32_16x16x32_bf16 v[60:63], v[156:159], v[172:175], v[60:63]
	v_mfma_f32_16x16x32_bf16 v[56:59], v[164:167], v[172:175], v[56:59]
	v_mfma_f32_16x16x32_bf16 v[44:47], v[156:159], v[180:183], v[44:47]
	v_mfma_f32_16x16x32_bf16 v[40:43], v[164:167], v[180:183], v[40:43]
	v_mfma_f32_16x16x32_bf16 v[28:31], v[156:159], v[188:191], v[28:31]
	v_mfma_f32_16x16x32_bf16 v[24:27], v[164:167], v[188:191], v[24:27]
	v_mfma_f32_16x16x32_bf16 v[12:15], v[156:159], v[196:199], v[12:15]
	v_mfma_f32_16x16x32_bf16 v[8:11], v[164:167], v[196:199], v[8:11]
	s_setprio 0
	s_barrier
	s_add_u32 s72, s48, 0x80000
	s_addc_u32 s73, s49, 0
	s_add_i32 s71, s82, s54
	s_mov_b32 m0, s71
	s_nop 0
	global_load_lds_dwordx4 v130, s[72:73]
	s_add_i32 m0, s71, 0x2000
	s_nop 0
	global_load_lds_dwordx4 v134, s[72:73]
	s_waitcnt vmcnt(6)
	s_barrier
; #define PG8_STAGE(bufoff, gbase, voff) do { _Pragma("unroll") for (int _i = 0; _i < 2; ++_i) \
;         __builtin_amdgcn_global_load_lds((const unsigned*)((const char*)(gbase) + (voff)[_i]), (LAS unsigned*)(lds + (bufoff) + ldsw + _i * 8192), 16, 0, 0); } while (0)
; #define PG8_LDA(dst, b, h) do { _Pragma("unroll") for (int m = 0; m < 4; ++m) _Pragma("unroll") for (int k = 0; k < 2; ++k) dst[m][k] = *(const LAS bf16x8*)(lds + PG8_SA(b, h) + aoff + m * 2048 + k * 1024); } while (0)
; #define PG8_LDB(dst, b, h) do { _Pragma("unroll") for (int n = 0; n < 2; ++n) _Pragma("unroll") for (int k = 0; k < 2; ++k) dst[n][k] = *(const LAS bf16x8*)(lds + PG8_SB(b, h) + boff + n * 2048 + k * 1024); } while (0)
; #define PG8_WAIT_V(n) asm volatile("s_waitcnt vmcnt(" #n ")" ::: "memory")
; #define PG8_WAIT_L(n) asm volatile("s_waitcnt lgkmcnt(" #n ")" ::: "memory")
; #define PG8_BAR __builtin_amdgcn_s_barrier()
; #define PG8_SCHED __builtin_amdgcn_sched_barrier(0)
; template <class Epi>
; __device__ __forceinline__ void gemm_phase(LAS unsigned char* lds, const bf16_t* A, int lda, const bf16_t* Bt, int ldb, int M, int N, int K, int asel, const Epi& E, const int fixed_round = -1) {
;     ...
;             PG8_BAR; PG8_WAIT_L(0); PG8_MMA(0, 1, At, B1); PG8_BAR;
;             PG8_LDA(At, 0, 1); PG8_STAGE(PG8_SA(0, 0), a2, voffA);
;             PG8_BAR; PG8_WAIT_L(0); PG8_MMA(1, 0, At, B0); PG8_BAR; PG8_SCHED;
;             PG8_STAGE(PG8_SB(0, 1), b2 + hstepB, voffB);
;             PG8_WAIT_V(6); PG8_BAR; PG8_MMA(1, 1, At, B1); PG8_BAR;
;             PG8_LDB(B0, 1, 0); PG8_SCHED; PG8_LDA(At, 1, 0); PG8_STAGE(PG8_SA(0, 1), a2 + hstepA, voffA);
;             PG8_WAIT_L(8); PG8_BAR; PG8_WAIT_L(0); PG8_MMA(0, 0, At, B0); PG8_BAR; PG8_SCHED;
;             PG8_LDB(B1, 1, 1); PG8_STAGE(PG8_SB(1, 0), b3, voffB);
;             PG8_BAR; PG8_WAIT_L(0); PG8_MMA(0, 1, At, B1); PG8_BAR;
;             PG8_LDA(At, 1, 1); PG8_STAGE(PG8_SA(1, 0), a3, voffA);
;             PG8_BAR; PG8_WAIT_L(0); PG8_MMA(1, 0, At, B0); PG8_BAR; PG8_SCHED;
;             PG8_STAGE(PG8_SB(1, 1), b3 + hstepB, voffB);
;             PG8_WAIT_V(6); PG8_BAR; PG8_MMA(1, 1, At, B1); PG8_BAR;
	s_setprio 1
	v_mfma_f32_16x16x32_bf16 v[52:55], v[202:205], v[168:171], v[52:55]
	v_mfma_f32_16x16x32_bf16 v[48:51], v[210:213], v[168:171], v[48:51]
	v_mfma_f32_16x16x32_bf16 v[36:39], v[202:205], v[176:179], v[36:39]
	v_mfma_f32_16x16x32_bf16 v[32:35], v[210:213], v[176:179], v[32:35]
	v_mfma_f32_16x16x32_bf16 v[20:23], v[202:205], v[184:187], v[20:23]
	v_mfma_f32_16x16x32_bf16 v[16:19], v[210:213], v[184:187], v[16:19]
	v_mfma_f32_16x16x32_bf16 v[4:7], v[202:205], v[192:195], v[4:7]
	v_mfma_f32_16x16x32_bf16 v[0:3], v[210:213], v[192:195], v[0:3]
	v_mfma_f32_16x16x32_bf16 v[52:55], v[206:209], v[172:175], v[52:55]
	v_mfma_f32_16x16x32_bf16 v[48:51], v[214:217], v[172:175], v[48:51]
	v_mfma_f32_16x16x32_bf16 v[36:39], v[206:209], v[180:183], v[36:39]
	v_mfma_f32_16x16x32_bf16 v[32:35], v[214:217], v[180:183], v[32:35]
	v_mfma_f32_16x16x32_bf16 v[20:23], v[206:209], v[188:191], v[20:23]
	v_mfma_f32_16x16x32_bf16 v[16:19], v[214:217], v[188:191], v[16:19]
	v_mfma_f32_16x16x32_bf16 v[4:7], v[206:209], v[196:199], v[4:7]
	v_mfma_f32_16x16x32_bf16 v[0:3], v[214:217], v[196:199], v[0:3]
	s_setprio 0
	v_add_u32_e32 v164, s83, v147
	s_barrier
	ds_read_b128 v[152:155], v164
	ds_read_b128 v[156:159], v164 offset:1024
	ds_read_b128 v[160:163], v164 offset:2048
	ds_read_b128 v[164:167], v164 offset:3072
	s_add_u32 s50, s50, 0x80000
	s_addc_u32 s51, s51, 0
	s_mov_b32 m0, s56
	ds_read_b128 v[168:171], v150 offset:32768
	ds_read_b128 v[172:175], v150 offset:33792
	ds_read_b128 v[176:179], v150 offset:34816
	ds_read_b128 v[180:183], v150 offset:35840
	ds_read_b128 v[184:187], v150 offset:36864
	ds_read_b128 v[188:191], v150 offset:37888
	ds_read_b128 v[192:195], v150 offset:38912
	ds_read_b128 v[196:199], v150 offset:39936
	global_load_lds_dwordx4 v128, s[50:51]
	s_mov_b32 m0, s57
	s_nop 0
	global_load_lds_dwordx4 v132, s[50:51]
	s_waitcnt lgkmcnt(8)
	s_barrier
	s_waitcnt lgkmcnt(0)
	s_setprio 1
	s_waitcnt lgkmcnt(0)
	v_mfma_f32_16x16x32_bf16 v[124:127], v[152:155], v[168:171], v[124:127]
	v_mfma_f32_16x16x32_bf16 v[120:123], v[160:163], v[168:171], v[120:123]
	v_mfma_f32_16x16x32_bf16 v[108:111], v[152:155], v[176:179], v[108:111]
	v_mfma_f32_16x16x32_bf16 v[104:107], v[160:163], v[176:179], v[104:107]
	v_mfma_f32_16x16x32_bf16 v[92:95], v[152:155], v[184:187], v[92:95]
	v_mfma_f32_16x16x32_bf16 v[88:91], v[160:163], v[184:187], v[88:91]
	v_mfma_f32_16x16x32_bf16 v[76:79], v[152:155], v[192:195], v[76:79]
	v_mfma_f32_16x16x32_bf16 v[72:75], v[160:163], v[192:195], v[72:75]
	v_mfma_f32_16x16x32_bf16 v[124:127], v[156:159], v[172:175], v[124:127]
	v_mfma_f32_16x16x32_bf16 v[120:123], v[164:167], v[172:175], v[120:123]
	v_mfma_f32_16x16x32_bf16 v[108:111], v[156:159], v[180:183], v[108:111]
	v_mfma_f32_16x16x32_bf16 v[104:107], v[164:167], v[180:183], v[104:107]
	v_mfma_f32_16x16x32_bf16 v[92:95], v[156:159], v[188:191], v[92:95]
	v_mfma_f32_16x16x32_bf16 v[88:91], v[164:167], v[188:191], v[88:91]
	v_mfma_f32_16x16x32_bf16 v[76:79], v[156:159], v[196:199], v[76:79]
	v_mfma_f32_16x16x32_bf16 v[72:75], v[164:167], v[196:199], v[72:75]
	s_setprio 0
	s_barrier
	s_add_i32 s50, s83, s54
	v_add_u32_e32 v214, s84, v147
	s_mov_b32 m0, s50
	ds_read_b128 v[202:205], v214
	ds_read_b128 v[206:209], v214 offset:1024
	ds_read_b128 v[210:213], v214 offset:2048
	ds_read_b128 v[214:217], v214 offset:3072
	global_load_lds_dwordx4 v130, s[98:99]
	s_add_i32 m0, s50, 0x2000
	s_nop 0
	global_load_lds_dwordx4 v134, s[98:99]
	s_barrier
	s_waitcnt lgkmcnt(0)
	s_setprio 1
	s_waitcnt lgkmcnt(0)
	v_mfma_f32_16x16x32_bf16 v[116:119], v[202:205], v[168:171], v[116:119]
	v_mfma_f32_16x16x32_bf16 v[112:115], v[210:213], v[168:171], v[112:115]
	v_mfma_f32_16x16x32_bf16 v[100:103], v[202:205], v[176:179], v[100:103]
	v_mfma_f32_16x16x32_bf16 v[96:99], v[210:213], v[176:179], v[96:99]
	v_mfma_f32_16x16x32_bf16 v[84:87], v[202:205], v[184:187], v[84:87]
	v_mfma_f32_16x16x32_bf16 v[80:83], v[210:213], v[184:187], v[80:83]
	v_mfma_f32_16x16x32_bf16 v[68:71], v[202:205], v[192:195], v[68:71]
	v_mfma_f32_16x16x32_bf16 v[64:67], v[210:213], v[192:195], v[64:67]
	v_mfma_f32_16x16x32_bf16 v[116:119], v[206:209], v[172:175], v[116:119]
	v_mfma_f32_16x16x32_bf16 v[112:115], v[214:217], v[172:175], v[112:115]
	v_mfma_f32_16x16x32_bf16 v[100:103], v[206:209], v[180:183], v[100:103]
	v_mfma_f32_16x16x32_bf16 v[96:99], v[214:217], v[180:183], v[96:99]
	v_mfma_f32_16x16x32_bf16 v[84:87], v[206:209], v[188:191], v[84:87]
	v_mfma_f32_16x16x32_bf16 v[80:83], v[214:217], v[188:191], v[80:83]
	v_mfma_f32_16x16x32_bf16 v[68:71], v[206:209], v[196:199], v[68:71]
	v_mfma_f32_16x16x32_bf16 v[64:67], v[214:217], v[196:199], v[64:67]
	s_setprio 0
	s_mov_b32 m0, s59
	s_barrier
	ds_read_b128 v[168:171], v150 offset:49152
	ds_read_b128 v[172:175], v150 offset:50176
	ds_read_b128 v[176:179], v150 offset:51200
	ds_read_b128 v[180:183], v150 offset:52224
	ds_read_b128 v[184:187], v150 offset:53248
	ds_read_b128 v[188:191], v150 offset:54272
	ds_read_b128 v[192:195], v150 offset:55296
	ds_read_b128 v[196:199], v150 offset:56320
	global_load_lds_dwordx4 v128, s[100:101]
	s_mov_b32 m0, s60
	s_nop 0
	global_load_lds_dwordx4 v132, s[100:101]
	s_barrier
; __device__ __forceinline__ unsigned cvt_pk_bf16(float lo, float hi) { const bf16x2_t r = __builtin_convertvector((f32x2){lo, hi}, bf16x2_t); return __builtin_bit_cast(unsigned, r); }
; #define PG8_STAGE(bufoff, gbase, voff) do { _Pragma("unroll") for (int _i = 0; _i < 2; ++_i) \
;         __builtin_amdgcn_global_load_lds((const unsigned*)((const char*)(gbase) + (voff)[_i]), (LAS unsigned*)(lds + (bufoff) + ldsw + _i * 8192), 16, 0, 0); } while (0)
; #define PG8_LDA(dst, b, h) do { _Pragma("unroll") for (int m = 0; m < 4; ++m) _Pragma("unroll") for (int k = 0; k < 2; ++k) dst[m][k] = *(const LAS bf16x8*)(lds + PG8_SA(b, h) + aoff + m * 2048 + k * 1024); } while (0)
; #define PG8_WAIT_V(n) asm volatile("s_waitcnt vmcnt(" #n ")" ::: "memory")
; #define PG8_WAIT_L(n) asm volatile("s_waitcnt lgkmcnt(" #n ")" ::: "memory")
; #define PG8_BAR __builtin_amdgcn_s_barrier()
; #define PG8_SCHED __builtin_amdgcn_sched_barrier(0)
; template <class Epi>
; __device__ __forceinline__ void gemm_phase(LAS unsigned char* lds, const bf16_t* A, int lda, const bf16_t* Bt, int ldb, int M, int N, int K, int asel, const Epi& E, const int fixed_round = -1) {
;     ...
;             PG8_BAR; PG8_WAIT_L(0); PG8_MMA(0, 1, At, B1); PG8_BAR;
;             PG8_LDA(At, 1, 1); PG8_STAGE(PG8_SA(1, 0), a3, voffA);
;             PG8_BAR; PG8_WAIT_L(0); PG8_MMA(1, 0, At, B0); PG8_BAR; PG8_SCHED;
;             PG8_STAGE(PG8_SB(1, 1), b3 + hstepB, voffB);
;             PG8_WAIT_V(6); PG8_BAR; PG8_MMA(1, 1, At, B1); PG8_BAR;
;     __device__ __forceinline__ void operator()(const AccT& acc, const Unit& u, int wr, int wc, int fr, int fq) const {
;         const int row0 = u.pm * BM + wr * 64 + fr, col0 = u.pn * BM + wc * 32 + 8 * fq;
; #pragma unroll
;         for (int ai = 0; ai < 2; ++ai)
; #pragma unroll
;             for (int m = 0; m < 4; ++m) { bf16_t* rowp = O + (size_t)(row0 + ai * HALF + m * 16) * DFF + col0;
; #pragma unroll
;                 for (int bj = 0; bj < 2; ++bj) { f32x4 v0 = acc[ai][bj][m][0], v1 = acc[ai][bj][m][1];
; #pragma unroll
;                     for (int j = 0; j < 4; ++j) { float a = fmaxf(v0[j], 0.f), b = fmaxf(v1[j], 0.f); v0[j] = a * a; v1[j] = b * b; }
;                     u32x4 w; w.x = cvt_pk_bf16(v0[0], v0[1]); w.y = cvt_pk_bf16(v0[2], v0[3]); w.z = cvt_pk_bf16(v1[0], v1[1]); w.w = cvt_pk_bf16(v1[2], v1[3]);
;                     *(u32x4*)(rowp + bj * HALF) = w; } }
	s_waitcnt lgkmcnt(0)
	s_setprio 1
	s_waitcnt lgkmcnt(0)
	v_mfma_f32_16x16x32_bf16 v[60:63], v[152:155], v[168:171], v[60:63]
	v_mfma_f32_16x16x32_bf16 v[56:59], v[160:163], v[168:171], v[56:59]
	v_mfma_f32_16x16x32_bf16 v[44:47], v[152:155], v[176:179], v[44:47]
	v_mfma_f32_16x16x32_bf16 v[40:43], v[160:163], v[176:179], v[40:43]
	v_mfma_f32_16x16x32_bf16 v[28:31], v[152:155], v[184:187], v[28:31]
	v_mfma_f32_16x16x32_bf16 v[24:27], v[160:163], v[184:187], v[24:27]
	v_mfma_f32_16x16x32_bf16 v[12:15], v[152:155], v[192:195], v[12:15]
	v_mfma_f32_16x16x32_bf16 v[8:11], v[160:163], v[192:195], v[8:11]
	v_mfma_f32_16x16x32_bf16 v[60:63], v[156:159], v[172:175], v[60:63]
	v_mfma_f32_16x16x32_bf16 v[56:59], v[164:167], v[172:175], v[56:59]
	v_mfma_f32_16x16x32_bf16 v[44:47], v[156:159], v[180:183], v[44:47]
	v_mfma_f32_16x16x32_bf16 v[40:43], v[164:167], v[180:183], v[40:43]
	v_mfma_f32_16x16x32_bf16 v[28:31], v[156:159], v[188:191], v[28:31]
	v_mfma_f32_16x16x32_bf16 v[24:27], v[164:167], v[188:191], v[24:27]
	v_mfma_f32_16x16x32_bf16 v[12:15], v[156:159], v[196:199], v[12:15]
	v_mfma_f32_16x16x32_bf16 v[8:11], v[164:167], v[196:199], v[8:11]
	s_setprio 0
	s_barrier
	s_add_u32 s48, s48, 0x80080
	s_addc_u32 s49, s49, 0
	s_add_i32 s50, s84, s54
	s_mov_b32 m0, s50
	s_nop 0
	global_load_lds_dwordx4 v130, s[48:49]
	s_add_i32 m0, s50, 0x2000
	s_nop 0
	global_load_lds_dwordx4 v134, s[48:49]
	s_waitcnt vmcnt(6)
	s_barrier
	s_setprio 1
	v_mfma_f32_16x16x32_bf16 v[52:55], v[202:205], v[168:171], v[52:55]
	v_mfma_f32_16x16x32_bf16 v[48:51], v[210:213], v[168:171], v[48:51]
	v_mfma_f32_16x16x32_bf16 v[36:39], v[202:205], v[176:179], v[36:39]
	v_mfma_f32_16x16x32_bf16 v[32:35], v[210:213], v[176:179], v[32:35]
	v_mfma_f32_16x16x32_bf16 v[20:23], v[202:205], v[184:187], v[20:23]
	v_mfma_f32_16x16x32_bf16 v[16:19], v[210:213], v[184:187], v[16:19]
	v_mfma_f32_16x16x32_bf16 v[4:7], v[202:205], v[192:195], v[4:7]
	v_mfma_f32_16x16x32_bf16 v[0:3], v[210:213], v[192:195], v[0:3]
	v_mfma_f32_16x16x32_bf16 v[52:55], v[206:209], v[172:175], v[52:55]
	v_mfma_f32_16x16x32_bf16 v[48:51], v[214:217], v[172:175], v[48:51]
	v_mfma_f32_16x16x32_bf16 v[36:39], v[206:209], v[180:183], v[36:39]
	v_mfma_f32_16x16x32_bf16 v[32:35], v[214:217], v[180:183], v[32:35]
	v_mfma_f32_16x16x32_bf16 v[20:23], v[206:209], v[188:191], v[20:23]
	v_mfma_f32_16x16x32_bf16 v[16:19], v[214:217], v[188:191], v[16:19]
	v_mfma_f32_16x16x32_bf16 v[4:7], v[206:209], v[196:199], v[4:7]
	v_mfma_f32_16x16x32_bf16 v[0:3], v[214:217], v[196:199], v[0:3]
	s_setprio 0
	s_add_i32 s70, s70, 2
	s_add_u32 s46, s46, 0x100
	s_addc_u32 s47, s47, 0
	s_add_u32 s68, s68, 0x100
	s_addc_u32 s69, s69, 0
	s_cmp_gt_u32 s70, 29
	s_barrier
	s_cbranch_scc0 .LBB0_1223
	v_lshl_add_u32 v152, s44, 8, v146
	v_lshl_or_b32 v144, s65, 8, v148
	v_ashrrev_i32_e32 v153, 31, v152
	v_readlane_b32 s46, v254, 60
	v_ashrrev_i32_e32 v145, 31, v144
	v_lshlrev_b64 v[154:155], 14, v[152:153]
	v_readlane_b32 s47, v254, 61
	v_lshl_add_u64 v[154:155], s[46:47], 0, v[154:155]
	v_lshlrev_b64 v[156:157], 1, v[144:145]
	v_max_f32_e32 v120, 0, v120
	v_max_f32_e32 v121, 0, v121
	v_lshl_add_u64 v[144:145], v[154:155], 0, v[156:157]
	v_pk_mul_f32 v[154:155], v[120:121], v[120:121]
	v_max_f32_e32 v121, v122, v122
	v_max_f32_e32 v120, v126, v126
	v_max_f32_e32 v122, 0, v121
	v_max_f32_e32 v121, v127, v127
	v_max_f32_e32 v124, 0, v124
	v_max_f32_e32 v125, 0, v125
	v_max_f32_e32 v120, 0, v120
	v_max_f32_e32 v121, 0, v121
	v_max_f32_e32 v123, 0, v123
	v_pk_mul_f32 v[124:125], v[124:125], v[124:125]
	v_pk_mul_f32 v[126:127], v[120:121], v[120:121]
	v_pk_mul_f32 v[158:159], v[122:123], v[122:123]
	v_cvt_pk_bf16_f32 v120, v124, v125
	v_cvt_pk_bf16_f32 v121, v126, v127
	v_cvt_pk_bf16_f32 v122, v154, v155
	v_cvt_pk_bf16_f32 v123, v158, v159
	v_max_f32_e32 v112, 0, v112
	v_max_f32_e32 v113, 0, v113
	global_store_dwordx4 v[144:145], v[120:123], off sc1
	s_nop 1
	v_pk_mul_f32 v[120:121], v[112:113], v[112:113]
	v_max_f32_e32 v113, v114, v114
	v_max_f32_e32 v112, v118, v118
	v_max_f32_e32 v114, 0, v113
	v_max_f32_e32 v113, v119, v119
	v_max_f32_e32 v116, 0, v116
	v_max_f32_e32 v117, 0, v117
	v_max_f32_e32 v112, 0, v112
	v_max_f32_e32 v113, 0, v113
	v_max_f32_e32 v115, 0, v115
	v_pk_mul_f32 v[116:117], v[116:117], v[116:117]
	v_pk_mul_f32 v[118:119], v[112:113], v[112:113]
	v_pk_mul_f32 v[122:123], v[114:115], v[114:115]
	v_cvt_pk_bf16_f32 v112, v116, v117
	v_cvt_pk_bf16_f32 v113, v118, v119
	v_cvt_pk_bf16_f32 v114, v120, v121
	v_cvt_pk_bf16_f32 v115, v122, v123
	v_max_f32_e32 v104, 0, v104
	v_max_f32_e32 v105, 0, v105
	global_store_dwordx4 v[144:145], v[112:115], off offset:256 sc1
	s_nop 1
	v_or_b32_e32 v112, 16, v152
	v_pk_mul_f32 v[114:115], v[104:105], v[104:105]
	v_max_f32_e32 v105, v106, v106
	v_ashrrev_i32_e32 v113, 31, v112
	v_max_f32_e32 v104, v110, v110
	v_max_f32_e32 v106, 0, v105
	v_max_f32_e32 v105, v111, v111
	v_lshlrev_b64 v[112:113], 14, v[112:113]
	v_max_f32_e32 v108, 0, v108
	v_max_f32_e32 v109, 0, v109
	v_max_f32_e32 v104, 0, v104
	v_max_f32_e32 v105, 0, v105
	v_max_f32_e32 v107, 0, v107
	v_lshl_add_u64 v[112:113], s[46:47], 0, v[112:113]
	v_pk_mul_f32 v[108:109], v[108:109], v[108:109]
	v_pk_mul_f32 v[110:111], v[104:105], v[104:105]
	v_pk_mul_f32 v[116:117], v[106:107], v[106:107]
	v_lshl_add_u64 v[112:113], v[112:113], 0, v[156:157]
	v_cvt_pk_bf16_f32 v104, v108, v109
	v_cvt_pk_bf16_f32 v105, v110, v111
	v_cvt_pk_bf16_f32 v106, v114, v115
	v_cvt_pk_bf16_f32 v107, v116, v117
	v_max_f32_e32 v96, 0, v96
	v_max_f32_e32 v97, 0, v97
	global_store_dwordx4 v[112:113], v[104:107], off sc1
	s_nop 1
	v_pk_mul_f32 v[104:105], v[96:97], v[96:97]
; __device__ __forceinline__ unsigned cvt_pk_bf16(float lo, float hi) { const bf16x2_t r = __builtin_convertvector((f32x2){lo, hi}, bf16x2_t); return __builtin_bit_cast(unsigned, r); }
;     __device__ __forceinline__ void operator()(const AccT& acc, const Unit& u, int wr, int wc, int fr, int fq) const {
;     ...
;         for (int ai = 0; ai < 2; ++ai)
; #pragma unroll
;             for (int m = 0; m < 4; ++m) { bf16_t* rowp = O + (size_t)(row0 + ai * HALF + m * 16) * DFF + col0;
; #pragma unroll
;                 for (int bj = 0; bj < 2; ++bj) { f32x4 v0 = acc[ai][bj][m][0], v1 = acc[ai][bj][m][1];
; #pragma unroll
;                     for (int j = 0; j < 4; ++j) { float a = fmaxf(v0[j], 0.f), b = fmaxf(v1[j], 0.f); v0[j] = a * a; v1[j] = b * b; }
;                     u32x4 w; w.x = cvt_pk_bf16(v0[0], v0[1]); w.y = cvt_pk_bf16(v0[2], v0[3]); w.z = cvt_pk_bf16(v1[0], v1[1]); w.w = cvt_pk_bf16(v1[2], v1[3]);
;                     *(u32x4*)(rowp + bj * HALF) = w; } }
	v_max_f32_e32 v97, v98, v98
	v_max_f32_e32 v96, v102, v102
	v_max_f32_e32 v98, 0, v97
	v_max_f32_e32 v97, v103, v103
	v_max_f32_e32 v100, 0, v100
	v_max_f32_e32 v101, 0, v101
	v_max_f32_e32 v96, 0, v96
	v_max_f32_e32 v97, 0, v97
	v_max_f32_e32 v99, 0, v99
	v_pk_mul_f32 v[100:101], v[100:101], v[100:101]
	v_pk_mul_f32 v[102:103], v[96:97], v[96:97]
	v_pk_mul_f32 v[106:107], v[98:99], v[98:99]
	v_cvt_pk_bf16_f32 v96, v100, v101
	v_cvt_pk_bf16_f32 v97, v102, v103
	v_cvt_pk_bf16_f32 v98, v104, v105
	v_cvt_pk_bf16_f32 v99, v106, v107
	v_max_f32_e32 v88, 0, v88
	v_max_f32_e32 v89, 0, v89
	global_store_dwordx4 v[112:113], v[96:99], off offset:256 sc1
	s_nop 1
	v_or_b32_e32 v96, 32, v152
	v_pk_mul_f32 v[98:99], v[88:89], v[88:89]
	v_max_f32_e32 v89, v90, v90
	v_ashrrev_i32_e32 v97, 31, v96
	v_max_f32_e32 v88, v94, v94
	v_max_f32_e32 v90, 0, v89
	v_max_f32_e32 v89, v95, v95
	v_lshlrev_b64 v[96:97], 14, v[96:97]
	v_max_f32_e32 v92, 0, v92
	v_max_f32_e32 v93, 0, v93
	v_max_f32_e32 v88, 0, v88
	v_max_f32_e32 v89, 0, v89
	v_max_f32_e32 v91, 0, v91
	v_lshl_add_u64 v[96:97], s[46:47], 0, v[96:97]
	v_pk_mul_f32 v[92:93], v[92:93], v[92:93]
	v_pk_mul_f32 v[94:95], v[88:89], v[88:89]
	v_pk_mul_f32 v[100:101], v[90:91], v[90:91]
	v_lshl_add_u64 v[96:97], v[96:97], 0, v[156:157]
	v_cvt_pk_bf16_f32 v88, v92, v93
	v_cvt_pk_bf16_f32 v89, v94, v95
	v_cvt_pk_bf16_f32 v90, v98, v99
	v_cvt_pk_bf16_f32 v91, v100, v101
	v_max_f32_e32 v80, 0, v80
	v_max_f32_e32 v81, 0, v81
	global_store_dwordx4 v[96:97], v[88:91], off sc1
	s_nop 1
	v_pk_mul_f32 v[88:89], v[80:81], v[80:81]
	v_max_f32_e32 v81, v82, v82
	v_max_f32_e32 v80, v86, v86
	v_max_f32_e32 v82, 0, v81
	v_max_f32_e32 v81, v87, v87
	v_max_f32_e32 v84, 0, v84
	v_max_f32_e32 v85, 0, v85
	v_max_f32_e32 v80, 0, v80
	v_max_f32_e32 v81, 0, v81
	v_max_f32_e32 v83, 0, v83
	v_pk_mul_f32 v[84:85], v[84:85], v[84:85]
	v_pk_mul_f32 v[86:87], v[80:81], v[80:81]
	v_pk_mul_f32 v[90:91], v[82:83], v[82:83]
	v_cvt_pk_bf16_f32 v80, v84, v85
	v_cvt_pk_bf16_f32 v81, v86, v87
	v_cvt_pk_bf16_f32 v82, v88, v89
	v_cvt_pk_bf16_f32 v83, v90, v91
	v_max_f32_e32 v72, 0, v72
	v_max_f32_e32 v73, 0, v73
	global_store_dwordx4 v[96:97], v[80:83], off offset:256 sc1
	s_nop 1
	v_or_b32_e32 v80, 48, v152
	v_pk_mul_f32 v[82:83], v[72:73], v[72:73]
	v_max_f32_e32 v73, v74, v74
	v_ashrrev_i32_e32 v81, 31, v80
	v_max_f32_e32 v72, v78, v78
	v_max_f32_e32 v74, 0, v73
	v_max_f32_e32 v73, v79, v79
	v_lshlrev_b64 v[80:81], 14, v[80:81]
	v_max_f32_e32 v76, 0, v76
	v_max_f32_e32 v77, 0, v77
	v_max_f32_e32 v72, 0, v72
	v_max_f32_e32 v73, 0, v73
	v_max_f32_e32 v75, 0, v75
	v_lshl_add_u64 v[80:81], s[46:47], 0, v[80:81]
	v_pk_mul_f32 v[76:77], v[76:77], v[76:77]
	v_pk_mul_f32 v[78:79], v[72:73], v[72:73]
	v_pk_mul_f32 v[84:85], v[74:75], v[74:75]
	v_lshl_add_u64 v[80:81], v[80:81], 0, v[156:157]
	v_cvt_pk_bf16_f32 v72, v76, v77
	v_cvt_pk_bf16_f32 v73, v78, v79
	v_cvt_pk_bf16_f32 v74, v82, v83
	v_cvt_pk_bf16_f32 v75, v84, v85
	v_max_f32_e32 v64, 0, v64
	v_max_f32_e32 v65, 0, v65
	global_store_dwordx4 v[80:81], v[72:75], off sc1
	s_nop 1
	v_pk_mul_f32 v[72:73], v[64:65], v[64:65]
	v_max_f32_e32 v65, v66, v66
	v_max_f32_e32 v64, v70, v70
	v_max_f32_e32 v66, 0, v65
	v_max_f32_e32 v65, v71, v71
	v_max_f32_e32 v68, 0, v68
	v_max_f32_e32 v69, 0, v69
	v_max_f32_e32 v64, 0, v64
	v_max_f32_e32 v65, 0, v65
	v_max_f32_e32 v67, 0, v67
	v_pk_mul_f32 v[68:69], v[68:69], v[68:69]
	v_pk_mul_f32 v[70:71], v[64:65], v[64:65]
	v_pk_mul_f32 v[74:75], v[66:67], v[66:67]
	v_cvt_pk_bf16_f32 v64, v68, v69
	v_cvt_pk_bf16_f32 v65, v70, v71
	v_cvt_pk_bf16_f32 v66, v72, v73
	v_cvt_pk_bf16_f32 v67, v74, v75
	v_max_f32_e32 v56, 0, v56
	v_max_f32_e32 v57, 0, v57
	global_store_dwordx4 v[80:81], v[64:67], off offset:256 sc1
	s_nop 1
	v_pk_mul_f32 v[66:67], v[56:57], v[56:57]
	v_max_f32_e32 v57, v58, v58
	v_max_f32_e32 v60, 0, v60
	v_max_f32_e32 v61, 0, v61
	v_max_f32_e32 v56, v62, v62
	v_max_f32_e32 v58, 0, v57
	v_max_f32_e32 v57, v63, v63
	v_pk_mul_f32 v[60:61], v[60:61], v[60:61]
	v_max_f32_e32 v56, 0, v56
	v_max_f32_e32 v57, 0, v57
	v_max_f32_e32 v59, 0, v59
	v_pk_mul_f32 v[62:63], v[56:57], v[56:57]
	v_pk_mul_f32 v[68:69], v[58:59], v[58:59]
	v_cvt_pk_bf16_f32 v56, v60, v61
	v_add_co_u32_e32 v60, vcc, s61, v144
	v_cvt_pk_bf16_f32 v57, v62, v63
	v_cvt_pk_bf16_f32 v58, v66, v67
	v_cvt_pk_bf16_f32 v59, v68, v69
	v_addc_co_u32_e32 v61, vcc, 0, v145, vcc
	v_max_f32_e32 v48, 0, v48
	v_max_f32_e32 v49, 0, v49
	global_store_dwordx4 v[60:61], v[56:59], off sc1
	s_nop 1
	v_pk_mul_f32 v[56:57], v[48:49], v[48:49]
	v_max_f32_e32 v49, v50, v50
	v_max_f32_e32 v48, v54, v54
	v_max_f32_e32 v50, 0, v49
	v_max_f32_e32 v49, v55, v55
	v_max_f32_e32 v52, 0, v52
	v_max_f32_e32 v53, 0, v53
	v_max_f32_e32 v48, 0, v48
	v_max_f32_e32 v49, 0, v49
	v_max_f32_e32 v51, 0, v51
	s_mov_b64 s[46:47], 0x200000
	v_pk_mul_f32 v[52:53], v[52:53], v[52:53]
	v_pk_mul_f32 v[54:55], v[48:49], v[48:49]
; __device__ __forceinline__ unsigned cvt_pk_bf16(float lo, float hi) { const bf16x2_t r = __builtin_convertvector((f32x2){lo, hi}, bf16x2_t); return __builtin_bit_cast(unsigned, r); }
; #define PG8_WAIT_V(n) asm volatile("s_waitcnt vmcnt(" #n ")" ::: "memory")
; #define PG8_BAR __builtin_amdgcn_s_barrier()
; template <class Epi>
; __device__ __forceinline__ void gemm_phase(LAS unsigned char* lds, const bf16_t* A, int lda, const bf16_t* Bt, int ldb, int M, int N, int K, int asel, const Epi& E, const int fixed_round = -1) {
;     ...
;         if (!has_next) break;
; #pragma unroll
;         for (int a = 0; a < 2; ++a)
; #pragma unroll
;             for (int b = 0; b < 2; ++b)
; #pragma unroll
;                 for (int m = 0; m < 4; ++m)
; #pragma unroll
;                     for (int n = 0; n < 2; ++n) acc[a][b][m][n] = (f32x4){0.f, 0.f, 0.f, 0.f};
;         cur = nxt; cA = nA; cB = nB; ++ui;
;     }
;     PG8_WAIT_V(0);
;     if (wr == 0) PG8_BAR;
;     PG8_BAR;
;     __device__ __forceinline__ void operator()(const AccT& acc, const Unit& u, int wr, int wc, int fr, int fq) const {
;     ...
;         for (int ai = 0; ai < 2; ++ai)
; #pragma unroll
;             for (int m = 0; m < 4; ++m) { bf16_t* rowp = O + (size_t)(row0 + ai * HALF + m * 16) * DFF + col0;
; #pragma unroll
;                 for (int bj = 0; bj < 2; ++bj) { f32x4 v0 = acc[ai][bj][m][0], v1 = acc[ai][bj][m][1];
; #pragma unroll
;                     for (int j = 0; j < 4; ++j) { float a = fmaxf(v0[j], 0.f), b = fmaxf(v1[j], 0.f); v0[j] = a * a; v1[j] = b * b; }
;                     u32x4 w; w.x = cvt_pk_bf16(v0[0], v0[1]); w.y = cvt_pk_bf16(v0[2], v0[3]); w.z = cvt_pk_bf16(v1[0], v1[1]); w.w = cvt_pk_bf16(v1[2], v1[3]);
;                     *(u32x4*)(rowp + bj * HALF) = w; } }
;     }
	v_pk_mul_f32 v[58:59], v[50:51], v[50:51]
	v_lshl_add_u64 v[64:65], v[144:145], 0, s[46:47]
	v_cvt_pk_bf16_f32 v48, v52, v53
	v_cvt_pk_bf16_f32 v49, v54, v55
	v_cvt_pk_bf16_f32 v50, v56, v57
	v_cvt_pk_bf16_f32 v51, v58, v59
	v_max_f32_e32 v40, 0, v40
	v_max_f32_e32 v41, 0, v41
	global_store_dwordx4 v[64:65], v[48:51], off offset:256 sc1
	s_nop 1
	v_pk_mul_f32 v[50:51], v[40:41], v[40:41]
	v_max_f32_e32 v41, v42, v42
	v_max_f32_e32 v44, 0, v44
	v_max_f32_e32 v45, 0, v45
	v_max_f32_e32 v40, v46, v46
	v_max_f32_e32 v42, 0, v41
	v_max_f32_e32 v41, v47, v47
	v_pk_mul_f32 v[44:45], v[44:45], v[44:45]
	v_max_f32_e32 v40, 0, v40
	v_max_f32_e32 v41, 0, v41
	v_max_f32_e32 v43, 0, v43
	v_pk_mul_f32 v[46:47], v[40:41], v[40:41]
	v_pk_mul_f32 v[52:53], v[42:43], v[42:43]
	v_cvt_pk_bf16_f32 v40, v44, v45
	v_add_co_u32_e32 v44, vcc, s62, v144
	v_cvt_pk_bf16_f32 v41, v46, v47
	v_cvt_pk_bf16_f32 v42, v50, v51
	v_cvt_pk_bf16_f32 v43, v52, v53
	v_addc_co_u32_e32 v45, vcc, 0, v145, vcc
	v_max_f32_e32 v32, 0, v32
	v_max_f32_e32 v33, 0, v33
	global_store_dwordx4 v[44:45], v[40:43], off sc1
	s_nop 1
	v_pk_mul_f32 v[40:41], v[32:33], v[32:33]
	v_max_f32_e32 v33, v34, v34
	v_max_f32_e32 v32, v38, v38
	v_max_f32_e32 v34, 0, v33
	v_max_f32_e32 v33, v39, v39
	v_max_f32_e32 v36, 0, v36
	v_max_f32_e32 v37, 0, v37
	v_max_f32_e32 v32, 0, v32
	v_max_f32_e32 v33, 0, v33
	v_max_f32_e32 v35, 0, v35
	v_pk_mul_f32 v[36:37], v[36:37], v[36:37]
	v_pk_mul_f32 v[38:39], v[32:33], v[32:33]
	v_pk_mul_f32 v[42:43], v[34:35], v[34:35]
	v_lshl_add_u64 v[48:49], v[144:145], 0, s[4:5]
	v_cvt_pk_bf16_f32 v32, v36, v37
	v_cvt_pk_bf16_f32 v33, v38, v39
	v_cvt_pk_bf16_f32 v34, v40, v41
	v_cvt_pk_bf16_f32 v35, v42, v43
	v_max_f32_e32 v24, 0, v24
	v_max_f32_e32 v25, 0, v25
	global_store_dwordx4 v[48:49], v[32:35], off offset:256 sc1
	s_nop 1
	v_pk_mul_f32 v[34:35], v[24:25], v[24:25]
	v_max_f32_e32 v25, v26, v26
	v_max_f32_e32 v28, 0, v28
	v_max_f32_e32 v29, 0, v29
	v_max_f32_e32 v24, v30, v30
	v_max_f32_e32 v26, 0, v25
	v_max_f32_e32 v25, v31, v31
	v_pk_mul_f32 v[28:29], v[28:29], v[28:29]
	v_max_f32_e32 v24, 0, v24
	v_max_f32_e32 v25, 0, v25
	v_max_f32_e32 v27, 0, v27
	v_pk_mul_f32 v[30:31], v[24:25], v[24:25]
	v_pk_mul_f32 v[36:37], v[26:27], v[26:27]
	v_cvt_pk_bf16_f32 v24, v28, v29
	v_add_co_u32_e32 v28, vcc, s63, v144
	v_cvt_pk_bf16_f32 v25, v30, v31
	v_cvt_pk_bf16_f32 v26, v34, v35
	v_cvt_pk_bf16_f32 v27, v36, v37
	v_addc_co_u32_e32 v29, vcc, 0, v145, vcc
	v_max_f32_e32 v16, 0, v16
	v_max_f32_e32 v17, 0, v17
	global_store_dwordx4 v[28:29], v[24:27], off sc1
	s_nop 1
	v_pk_mul_f32 v[24:25], v[16:17], v[16:17]
	v_max_f32_e32 v17, v18, v18
	v_max_f32_e32 v16, v22, v22
	v_max_f32_e32 v18, 0, v17
	v_max_f32_e32 v17, v23, v23
	v_max_f32_e32 v20, 0, v20
	v_max_f32_e32 v21, 0, v21
	v_max_f32_e32 v16, 0, v16
	v_max_f32_e32 v17, 0, v17
	v_max_f32_e32 v19, 0, v19
	v_pk_mul_f32 v[20:21], v[20:21], v[20:21]
	v_pk_mul_f32 v[22:23], v[16:17], v[16:17]
	v_pk_mul_f32 v[26:27], v[18:19], v[18:19]
	v_lshl_add_u64 v[32:33], v[144:145], 0, s[6:7]
	v_cvt_pk_bf16_f32 v16, v20, v21
	v_cvt_pk_bf16_f32 v17, v22, v23
	v_cvt_pk_bf16_f32 v18, v24, v25
	v_cvt_pk_bf16_f32 v19, v26, v27
	v_max_f32_e32 v8, 0, v8
	v_max_f32_e32 v9, 0, v9
	global_store_dwordx4 v[32:33], v[16:19], off offset:256 sc1
	s_nop 1
	v_pk_mul_f32 v[18:19], v[8:9], v[8:9]
	v_max_f32_e32 v9, v10, v10
	v_max_f32_e32 v12, 0, v12
	v_max_f32_e32 v13, 0, v13
	v_max_f32_e32 v8, v14, v14
	v_max_f32_e32 v10, 0, v9
	v_max_f32_e32 v9, v15, v15
	v_pk_mul_f32 v[12:13], v[12:13], v[12:13]
	v_max_f32_e32 v8, 0, v8
	v_max_f32_e32 v9, 0, v9
	v_max_f32_e32 v11, 0, v11
	v_pk_mul_f32 v[14:15], v[8:9], v[8:9]
	v_pk_mul_f32 v[20:21], v[10:11], v[10:11]
	v_cvt_pk_bf16_f32 v8, v12, v13
	v_add_co_u32_e32 v12, vcc, s64, v144
	v_cvt_pk_bf16_f32 v9, v14, v15
	v_cvt_pk_bf16_f32 v10, v18, v19
	v_cvt_pk_bf16_f32 v11, v20, v21
	v_addc_co_u32_e32 v13, vcc, 0, v145, vcc
	v_max_f32_e32 v0, 0, v0
	v_max_f32_e32 v1, 0, v1
	global_store_dwordx4 v[12:13], v[8:11], off sc1
	s_nop 1
	v_pk_mul_f32 v[8:9], v[0:1], v[0:1]
	v_max_f32_e32 v1, v2, v2
	v_max_f32_e32 v0, v6, v6
	v_max_f32_e32 v2, 0, v1
	v_max_f32_e32 v1, v7, v7
	v_max_f32_e32 v4, 0, v4
	v_max_f32_e32 v5, 0, v5
	v_max_f32_e32 v0, 0, v0
	v_max_f32_e32 v1, 0, v1
	v_max_f32_e32 v3, 0, v3
	v_pk_mul_f32 v[4:5], v[4:5], v[4:5]
	v_pk_mul_f32 v[6:7], v[0:1], v[0:1]
	v_pk_mul_f32 v[10:11], v[2:3], v[2:3]
	v_lshl_add_u64 v[16:17], v[144:145], 0, s[22:23]
	v_cvt_pk_bf16_f32 v0, v4, v5
	v_cvt_pk_bf16_f32 v1, v6, v7
	v_cvt_pk_bf16_f32 v2, v8, v9
	v_cvt_pk_bf16_f32 v3, v10, v11
	s_and_b64 vcc, exec, s[0:1]
	s_mov_b32 s65, s24
	s_mov_b32 s44, s28
	s_mov_b64 s[48:49], s[42:43]
	s_mov_b64 s[46:47], s[40:41]
	s_mov_b64 s[70:71], s[26:27]
	global_store_dwordx4 v[16:17], v[0:3], off offset:256 sc1
	s_cbranch_vccz .LBB0_1216
	s_waitcnt vmcnt(0)
	s_cmpk_gt_u32 s33, 0xff
	s_cbranch_scc1 .LBB0_1227
	s_barrier
